# merge gate loads as dwordx2 + permlane16/32 swaps (half the gather instructions) on top of batched epilogues
# speedup vs baseline: 1.0612x; 1.0189x over previous
; DI bf16x4 pack4(float a, float b, float c, float d) { u32x2v u; u.x = pk2(a, b); u.y = pk2(c, d); return __builtin_bit_cast(bf16x4, u); }
;   DI void operator()(const f32x4 (&acc)[2][2][4][2], const pg8::Unit& u, int wr, int wc, int fr, int fq) const {
;     bf16_t* MERGED = (reinterpret_cast<bf16_t*>(p.ws + OFF_GA));
; #pragma unroll
;     for (int ai = 0; ai < 2; ++ai)
; #pragma unroll
;       for (int m = 0; m < 4; ++m) {
;         const int row = u.pm * 256 + 128 * ai + 64 * wr + 16 * m + fr;
; #pragma unroll
;         for (int bj = 0; bj < 2; ++bj)
; #pragma unroll
;           for (int n = 0; n < 2; ++n) {
;             const size_t idx = (size_t)row * 1024 + u.pn * 256 + 128 * bj + 32 * wc + 16 * n + 4 * fq;
;             const f32x4 a = acc[ai][bj][m][n];
;             if (MODE == 0) {
;               const unsigned g = *reinterpret_cast<const unsigned*>(reinterpret_cast<const unsigned char*>(p.ws + OFF_RB) + idx);
;               const float k = 1.f / 255.f;
;               st4(MERGED + idx, pack4((float)(g & 255u) * k * a[0], (float)((g >> 8) & 255u) * k * a[1], (float)((g >> 16) & 255u) * k * a[2], (float)(g >> 24) * k * a[3]));
.LBB0_2731:
	v_lshl_or_b32 v16, v148, 10, v138
	v_readlane_b32 s12, v250, 30
	v_readlane_b32 s13, v250, 31
	s_or_b32 s56, s29, s10
	s_mov_b32 s14, 0x3b808081
	v_or_b32_e32 v16, s56, v16
	v_lshlrev_b32_e32 v18, 1, v16
	v_add_u32_e32 v19, v16, v138
	s_add_u32 s56, s48, 0x0
	s_addc_u32 s57, s49, 0
	global_load_dwordx2 v[204:205], v19, s[56:57]
	global_load_dwordx2 v[206:207], v19, s[56:57] offset:128
	s_add_u32 s58, s48, 0x4000
	s_addc_u32 s59, s49, 0
	global_load_dwordx2 v[208:209], v19, s[58:59]
	global_load_dwordx2 v[210:211], v19, s[58:59] offset:128
	s_add_u32 s56, s48, 0x8000
	s_addc_u32 s57, s49, 0
	global_load_dwordx2 v[212:213], v19, s[56:57]
	global_load_dwordx2 v[214:215], v19, s[56:57] offset:128
	s_add_u32 s58, s48, 0xc000
	s_addc_u32 s59, s49, 0
	global_load_dwordx2 v[216:217], v19, s[58:59]
	global_load_dwordx2 v[218:219], v19, s[58:59] offset:128
	s_add_u32 s56, s48, 0x20000
	s_addc_u32 s57, s49, 0
	global_load_dwordx2 v[220:221], v19, s[56:57]
	global_load_dwordx2 v[222:223], v19, s[56:57] offset:128
	s_add_u32 s58, s48, 0x24000
	s_addc_u32 s59, s49, 0
	global_load_dwordx2 v[224:225], v19, s[58:59]
	global_load_dwordx2 v[226:227], v19, s[58:59] offset:128
	s_add_u32 s56, s48, 0x28000
	s_addc_u32 s57, s49, 0
	global_load_dwordx2 v[228:229], v19, s[56:57]
	global_load_dwordx2 v[230:231], v19, s[56:57] offset:128
	s_add_u32 s58, s48, 0x2c000
	s_addc_u32 s59, s49, 0
	global_load_dwordx2 v[232:233], v19, s[58:59]
	global_load_dwordx2 v[234:235], v19, s[58:59] offset:128
	s_add_u32 s60, s12, 0x0
	s_addc_u32 s61, s13, 0
	s_waitcnt vmcnt(15)
	v_permlane16_swap_b32_e32 v204, v205
	s_nop 1
	v_permlane32_swap_b32_e32 v204, v205
	v_cvt_f32_ubyte1_e32 v155, v204
	v_cvt_f32_ubyte0_e32 v154, v204
	v_cvt_f32_ubyte3_e32 v157, v204
	v_cvt_f32_ubyte2_e32 v156, v204
	v_pk_mul_f32 v[154:155], v[154:155], s[14:15] op_sel_hi:[1,0]
	v_pk_mul_f32 v[156:157], v[156:157], s[14:15] op_sel_hi:[1,0]
	v_pk_mul_f32 v[130:131], v[130:131], v[154:155]
	v_pk_mul_f32 v[132:133], v[132:133], v[156:157]
	v_cvt_pk_bf16_f32 v130, v130, v131
	v_cvt_pk_bf16_f32 v131, v132, v133
	global_store_dwordx2 v18, v[130:131], s[60:61]
	v_cvt_f32_ubyte1_e32 v155, v205
	v_cvt_f32_ubyte0_e32 v154, v205
	v_cvt_f32_ubyte3_e32 v157, v205
	v_cvt_f32_ubyte2_e32 v156, v205
	v_pk_mul_f32 v[154:155], v[154:155], s[14:15] op_sel_hi:[1,0]
	v_pk_mul_f32 v[156:157], v[156:157], s[14:15] op_sel_hi:[1,0]
	v_pk_mul_f32 v[126:127], v[126:127], v[154:155]
	v_pk_mul_f32 v[128:129], v[128:129], v[156:157]
	v_cvt_pk_bf16_f32 v126, v126, v127
	v_cvt_pk_bf16_f32 v127, v128, v129
	global_store_dwordx2 v18, v[126:127], s[60:61] offset:32
	s_waitcnt vmcnt(16)
	v_permlane16_swap_b32_e32 v206, v207
	s_nop 1
	v_permlane32_swap_b32_e32 v206, v207
	v_cvt_f32_ubyte1_e32 v155, v206
	v_cvt_f32_ubyte0_e32 v154, v206
	v_cvt_f32_ubyte3_e32 v157, v206
	v_cvt_f32_ubyte2_e32 v156, v206
	v_pk_mul_f32 v[154:155], v[154:155], s[14:15] op_sel_hi:[1,0]
	v_pk_mul_f32 v[156:157], v[156:157], s[14:15] op_sel_hi:[1,0]
	v_pk_mul_f32 v[122:123], v[122:123], v[154:155]
	v_pk_mul_f32 v[124:125], v[124:125], v[156:157]
	v_cvt_pk_bf16_f32 v122, v122, v123
	v_cvt_pk_bf16_f32 v123, v124, v125
	global_store_dwordx2 v18, v[122:123], s[60:61] offset:256
	v_cvt_f32_ubyte1_e32 v155, v207
	v_cvt_f32_ubyte0_e32 v154, v207
	v_cvt_f32_ubyte3_e32 v157, v207
	v_cvt_f32_ubyte2_e32 v156, v207
	v_pk_mul_f32 v[154:155], v[154:155], s[14:15] op_sel_hi:[1,0]
	v_pk_mul_f32 v[156:157], v[156:157], s[14:15] op_sel_hi:[1,0]
	v_pk_mul_f32 v[118:119], v[118:119], v[154:155]
	v_pk_mul_f32 v[120:121], v[120:121], v[156:157]
	v_cvt_pk_bf16_f32 v118, v118, v119
	v_cvt_pk_bf16_f32 v119, v120, v121
	global_store_dwordx2 v18, v[118:119], s[60:61] offset:288
	s_add_u32 s62, s12, 0x8000
	s_addc_u32 s63, s13, 0
	s_waitcnt vmcnt(17)
	v_permlane16_swap_b32_e32 v208, v209
	s_nop 1
	v_permlane32_swap_b32_e32 v208, v209
	v_cvt_f32_ubyte1_e32 v155, v208
	v_cvt_f32_ubyte0_e32 v154, v208
	v_cvt_f32_ubyte3_e32 v157, v208
	v_cvt_f32_ubyte2_e32 v156, v208
	v_pk_mul_f32 v[154:155], v[154:155], s[14:15] op_sel_hi:[1,0]
	v_pk_mul_f32 v[156:157], v[156:157], s[14:15] op_sel_hi:[1,0]
	v_pk_mul_f32 v[114:115], v[114:115], v[154:155]
	v_pk_mul_f32 v[116:117], v[116:117], v[156:157]
	v_cvt_pk_bf16_f32 v114, v114, v115
	v_cvt_pk_bf16_f32 v115, v116, v117
	global_store_dwordx2 v18, v[114:115], s[62:63]
	v_cvt_f32_ubyte1_e32 v155, v209
	v_cvt_f32_ubyte0_e32 v154, v209
	v_cvt_f32_ubyte3_e32 v157, v209
	v_cvt_f32_ubyte2_e32 v156, v209
	v_pk_mul_f32 v[154:155], v[154:155], s[14:15] op_sel_hi:[1,0]
	v_pk_mul_f32 v[156:157], v[156:157], s[14:15] op_sel_hi:[1,0]
	v_pk_mul_f32 v[110:111], v[110:111], v[154:155]
	v_pk_mul_f32 v[112:113], v[112:113], v[156:157]
	v_cvt_pk_bf16_f32 v110, v110, v111
	v_cvt_pk_bf16_f32 v111, v112, v113
	global_store_dwordx2 v18, v[110:111], s[62:63] offset:32
	s_waitcnt vmcnt(18)
	v_permlane16_swap_b32_e32 v210, v211
	s_nop 1
	v_permlane32_swap_b32_e32 v210, v211
	v_cvt_f32_ubyte1_e32 v155, v210
	v_cvt_f32_ubyte0_e32 v154, v210
	v_cvt_f32_ubyte3_e32 v157, v210
	v_cvt_f32_ubyte2_e32 v156, v210
	v_pk_mul_f32 v[154:155], v[154:155], s[14:15] op_sel_hi:[1,0]
	v_pk_mul_f32 v[156:157], v[156:157], s[14:15] op_sel_hi:[1,0]
	v_pk_mul_f32 v[106:107], v[106:107], v[154:155]
	v_pk_mul_f32 v[108:109], v[108:109], v[156:157]
	v_cvt_pk_bf16_f32 v106, v106, v107
	v_cvt_pk_bf16_f32 v107, v108, v109
	global_store_dwordx2 v18, v[106:107], s[62:63] offset:256
	v_cvt_f32_ubyte1_e32 v155, v211
	v_cvt_f32_ubyte0_e32 v154, v211
	v_cvt_f32_ubyte3_e32 v157, v211
	v_cvt_f32_ubyte2_e32 v156, v211
	v_pk_mul_f32 v[154:155], v[154:155], s[14:15] op_sel_hi:[1,0]
	v_pk_mul_f32 v[156:157], v[156:157], s[14:15] op_sel_hi:[1,0]
	v_pk_mul_f32 v[102:103], v[102:103], v[154:155]
	v_pk_mul_f32 v[104:105], v[104:105], v[156:157]
	v_cvt_pk_bf16_f32 v102, v102, v103
	v_cvt_pk_bf16_f32 v103, v104, v105
	global_store_dwordx2 v18, v[102:103], s[62:63] offset:288
	s_add_u32 s60, s12, 0x10000
	s_addc_u32 s61, s13, 0
	s_waitcnt vmcnt(19)
; DI bf16x4 pack4(float a, float b, float c, float d) { u32x2v u; u.x = pk2(a, b); u.y = pk2(c, d); return __builtin_bit_cast(bf16x4, u); }
;   DI void operator()(const f32x4 (&acc)[2][2][4][2], const pg8::Unit& u, int wr, int wc, int fr, int fq) const {
;     bf16_t* MERGED = (reinterpret_cast<bf16_t*>(p.ws + OFF_GA));
; #pragma unroll
;     for (int ai = 0; ai < 2; ++ai)
; #pragma unroll
;       for (int m = 0; m < 4; ++m) {
;         const int row = u.pm * 256 + 128 * ai + 64 * wr + 16 * m + fr;
; #pragma unroll
;         for (int bj = 0; bj < 2; ++bj)
; #pragma unroll
;           for (int n = 0; n < 2; ++n) {
;             const size_t idx = (size_t)row * 1024 + u.pn * 256 + 128 * bj + 32 * wc + 16 * n + 4 * fq;
;             const f32x4 a = acc[ai][bj][m][n];
;             if (MODE == 0) {
;               const unsigned g = *reinterpret_cast<const unsigned*>(reinterpret_cast<const unsigned char*>(p.ws + OFF_RB) + idx);
;               const float k = 1.f / 255.f;
;               st4(MERGED + idx, pack4((float)(g & 255u) * k * a[0], (float)((g >> 8) & 255u) * k * a[1], (float)((g >> 16) & 255u) * k * a[2], (float)(g >> 24) * k * a[3]));
	v_permlane16_swap_b32_e32 v212, v213
	s_nop 1
	v_permlane32_swap_b32_e32 v212, v213
	v_cvt_f32_ubyte1_e32 v155, v212
	v_cvt_f32_ubyte0_e32 v154, v212
	v_cvt_f32_ubyte3_e32 v157, v212
	v_cvt_f32_ubyte2_e32 v156, v212
	v_pk_mul_f32 v[154:155], v[154:155], s[14:15] op_sel_hi:[1,0]
	v_pk_mul_f32 v[156:157], v[156:157], s[14:15] op_sel_hi:[1,0]
	v_pk_mul_f32 v[98:99], v[98:99], v[154:155]
	v_pk_mul_f32 v[100:101], v[100:101], v[156:157]
	v_cvt_pk_bf16_f32 v98, v98, v99
	v_cvt_pk_bf16_f32 v99, v100, v101
	global_store_dwordx2 v18, v[98:99], s[60:61]
	v_cvt_f32_ubyte1_e32 v155, v213
	v_cvt_f32_ubyte0_e32 v154, v213
	v_cvt_f32_ubyte3_e32 v157, v213
	v_cvt_f32_ubyte2_e32 v156, v213
	v_pk_mul_f32 v[154:155], v[154:155], s[14:15] op_sel_hi:[1,0]
	v_pk_mul_f32 v[156:157], v[156:157], s[14:15] op_sel_hi:[1,0]
	v_pk_mul_f32 v[94:95], v[94:95], v[154:155]
	v_pk_mul_f32 v[96:97], v[96:97], v[156:157]
	v_cvt_pk_bf16_f32 v94, v94, v95
	v_cvt_pk_bf16_f32 v95, v96, v97
	global_store_dwordx2 v18, v[94:95], s[60:61] offset:32
	s_waitcnt vmcnt(20)
	v_permlane16_swap_b32_e32 v214, v215
	s_nop 1
	v_permlane32_swap_b32_e32 v214, v215
	v_cvt_f32_ubyte1_e32 v155, v214
	v_cvt_f32_ubyte0_e32 v154, v214
	v_cvt_f32_ubyte3_e32 v157, v214
	v_cvt_f32_ubyte2_e32 v156, v214
	v_pk_mul_f32 v[154:155], v[154:155], s[14:15] op_sel_hi:[1,0]
	v_pk_mul_f32 v[156:157], v[156:157], s[14:15] op_sel_hi:[1,0]
	v_pk_mul_f32 v[90:91], v[90:91], v[154:155]
	v_pk_mul_f32 v[92:93], v[92:93], v[156:157]
	v_cvt_pk_bf16_f32 v90, v90, v91
	v_cvt_pk_bf16_f32 v91, v92, v93
	global_store_dwordx2 v18, v[90:91], s[60:61] offset:256
	v_cvt_f32_ubyte1_e32 v155, v215
	v_cvt_f32_ubyte0_e32 v154, v215
	v_cvt_f32_ubyte3_e32 v157, v215
	v_cvt_f32_ubyte2_e32 v156, v215
	v_pk_mul_f32 v[154:155], v[154:155], s[14:15] op_sel_hi:[1,0]
	v_pk_mul_f32 v[156:157], v[156:157], s[14:15] op_sel_hi:[1,0]
	v_pk_mul_f32 v[86:87], v[86:87], v[154:155]
	v_pk_mul_f32 v[88:89], v[88:89], v[156:157]
	v_cvt_pk_bf16_f32 v86, v86, v87
	v_cvt_pk_bf16_f32 v87, v88, v89
	global_store_dwordx2 v18, v[86:87], s[60:61] offset:288
	s_add_u32 s62, s12, 0x18000
	s_addc_u32 s63, s13, 0
	s_waitcnt vmcnt(21)
	v_permlane16_swap_b32_e32 v216, v217
	s_nop 1
	v_permlane32_swap_b32_e32 v216, v217
	v_cvt_f32_ubyte1_e32 v155, v216
	v_cvt_f32_ubyte0_e32 v154, v216
	v_cvt_f32_ubyte3_e32 v157, v216
	v_cvt_f32_ubyte2_e32 v156, v216
	v_pk_mul_f32 v[154:155], v[154:155], s[14:15] op_sel_hi:[1,0]
	v_pk_mul_f32 v[156:157], v[156:157], s[14:15] op_sel_hi:[1,0]
	v_pk_mul_f32 v[82:83], v[82:83], v[154:155]
	v_pk_mul_f32 v[84:85], v[84:85], v[156:157]
	v_cvt_pk_bf16_f32 v82, v82, v83
	v_cvt_pk_bf16_f32 v83, v84, v85
	global_store_dwordx2 v18, v[82:83], s[62:63]
	v_cvt_f32_ubyte1_e32 v155, v217
	v_cvt_f32_ubyte0_e32 v154, v217
	v_cvt_f32_ubyte3_e32 v157, v217
	v_cvt_f32_ubyte2_e32 v156, v217
	v_pk_mul_f32 v[154:155], v[154:155], s[14:15] op_sel_hi:[1,0]
	v_pk_mul_f32 v[156:157], v[156:157], s[14:15] op_sel_hi:[1,0]
	v_pk_mul_f32 v[78:79], v[78:79], v[154:155]
	v_pk_mul_f32 v[80:81], v[80:81], v[156:157]
	v_cvt_pk_bf16_f32 v78, v78, v79
	v_cvt_pk_bf16_f32 v79, v80, v81
	global_store_dwordx2 v18, v[78:79], s[62:63] offset:32
	s_waitcnt vmcnt(22)
	v_permlane16_swap_b32_e32 v218, v219
	s_nop 1
	v_permlane32_swap_b32_e32 v218, v219
	v_cvt_f32_ubyte1_e32 v155, v218
	v_cvt_f32_ubyte0_e32 v154, v218
	v_cvt_f32_ubyte3_e32 v157, v218
	v_cvt_f32_ubyte2_e32 v156, v218
	v_pk_mul_f32 v[154:155], v[154:155], s[14:15] op_sel_hi:[1,0]
	v_pk_mul_f32 v[156:157], v[156:157], s[14:15] op_sel_hi:[1,0]
	v_pk_mul_f32 v[74:75], v[74:75], v[154:155]
	v_pk_mul_f32 v[76:77], v[76:77], v[156:157]
	v_cvt_pk_bf16_f32 v74, v74, v75
	v_cvt_pk_bf16_f32 v75, v76, v77
	global_store_dwordx2 v18, v[74:75], s[62:63] offset:256
	v_cvt_f32_ubyte1_e32 v155, v219
	v_cvt_f32_ubyte0_e32 v154, v219
	v_cvt_f32_ubyte3_e32 v157, v219
	v_cvt_f32_ubyte2_e32 v156, v219
	v_pk_mul_f32 v[154:155], v[154:155], s[14:15] op_sel_hi:[1,0]
	v_pk_mul_f32 v[156:157], v[156:157], s[14:15] op_sel_hi:[1,0]
	v_pk_mul_f32 v[70:71], v[70:71], v[154:155]
	v_pk_mul_f32 v[72:73], v[72:73], v[156:157]
	v_cvt_pk_bf16_f32 v70, v70, v71
	v_cvt_pk_bf16_f32 v71, v72, v73
	global_store_dwordx2 v18, v[70:71], s[62:63] offset:288
	s_add_u32 s60, s12, 0x40000
	s_addc_u32 s61, s13, 0
	s_waitcnt vmcnt(23)
	v_permlane16_swap_b32_e32 v220, v221
	s_nop 1
	v_permlane32_swap_b32_e32 v220, v221
	v_cvt_f32_ubyte1_e32 v155, v220
	v_cvt_f32_ubyte0_e32 v154, v220
	v_cvt_f32_ubyte3_e32 v157, v220
	v_cvt_f32_ubyte2_e32 v156, v220
	v_pk_mul_f32 v[154:155], v[154:155], s[14:15] op_sel_hi:[1,0]
	v_pk_mul_f32 v[156:157], v[156:157], s[14:15] op_sel_hi:[1,0]
	v_pk_mul_f32 v[66:67], v[66:67], v[154:155]
	v_pk_mul_f32 v[68:69], v[68:69], v[156:157]
	v_cvt_pk_bf16_f32 v66, v66, v67
	v_cvt_pk_bf16_f32 v67, v68, v69
	global_store_dwordx2 v18, v[66:67], s[60:61]
	v_cvt_f32_ubyte1_e32 v155, v221
	v_cvt_f32_ubyte0_e32 v154, v221
	v_cvt_f32_ubyte3_e32 v157, v221
	v_cvt_f32_ubyte2_e32 v156, v221
	v_pk_mul_f32 v[154:155], v[154:155], s[14:15] op_sel_hi:[1,0]
	v_pk_mul_f32 v[156:157], v[156:157], s[14:15] op_sel_hi:[1,0]
	v_pk_mul_f32 v[62:63], v[62:63], v[154:155]
	v_pk_mul_f32 v[64:65], v[64:65], v[156:157]
	v_cvt_pk_bf16_f32 v62, v62, v63
	v_cvt_pk_bf16_f32 v63, v64, v65
	global_store_dwordx2 v18, v[62:63], s[60:61] offset:32
	s_waitcnt vmcnt(24)
; DI bf16x4 pack4(float a, float b, float c, float d) { u32x2v u; u.x = pk2(a, b); u.y = pk2(c, d); return __builtin_bit_cast(bf16x4, u); }
;   DI void operator()(const f32x4 (&acc)[2][2][4][2], const pg8::Unit& u, int wr, int wc, int fr, int fq) const {
;     bf16_t* MERGED = (reinterpret_cast<bf16_t*>(p.ws + OFF_GA));
; #pragma unroll
;     for (int ai = 0; ai < 2; ++ai)
; #pragma unroll
;       for (int m = 0; m < 4; ++m) {
;         const int row = u.pm * 256 + 128 * ai + 64 * wr + 16 * m + fr;
; #pragma unroll
;         for (int bj = 0; bj < 2; ++bj)
; #pragma unroll
;           for (int n = 0; n < 2; ++n) {
;             const size_t idx = (size_t)row * 1024 + u.pn * 256 + 128 * bj + 32 * wc + 16 * n + 4 * fq;
;             const f32x4 a = acc[ai][bj][m][n];
;             if (MODE == 0) {
;               const unsigned g = *reinterpret_cast<const unsigned*>(reinterpret_cast<const unsigned char*>(p.ws + OFF_RB) + idx);
;               const float k = 1.f / 255.f;
;               st4(MERGED + idx, pack4((float)(g & 255u) * k * a[0], (float)((g >> 8) & 255u) * k * a[1], (float)((g >> 16) & 255u) * k * a[2], (float)(g >> 24) * k * a[3]));
	v_permlane16_swap_b32_e32 v222, v223
	s_nop 1
	v_permlane32_swap_b32_e32 v222, v223
	v_cvt_f32_ubyte1_e32 v155, v222
	v_cvt_f32_ubyte0_e32 v154, v222
	v_cvt_f32_ubyte3_e32 v157, v222
	v_cvt_f32_ubyte2_e32 v156, v222
	v_pk_mul_f32 v[154:155], v[154:155], s[14:15] op_sel_hi:[1,0]
	v_pk_mul_f32 v[156:157], v[156:157], s[14:15] op_sel_hi:[1,0]
	v_pk_mul_f32 v[58:59], v[58:59], v[154:155]
	v_pk_mul_f32 v[60:61], v[60:61], v[156:157]
	v_cvt_pk_bf16_f32 v58, v58, v59
	v_cvt_pk_bf16_f32 v59, v60, v61
	global_store_dwordx2 v18, v[58:59], s[60:61] offset:256
	v_cvt_f32_ubyte1_e32 v155, v223
	v_cvt_f32_ubyte0_e32 v154, v223
	v_cvt_f32_ubyte3_e32 v157, v223
	v_cvt_f32_ubyte2_e32 v156, v223
	v_pk_mul_f32 v[154:155], v[154:155], s[14:15] op_sel_hi:[1,0]
	v_pk_mul_f32 v[156:157], v[156:157], s[14:15] op_sel_hi:[1,0]
	v_pk_mul_f32 v[54:55], v[54:55], v[154:155]
	v_pk_mul_f32 v[56:57], v[56:57], v[156:157]
	v_cvt_pk_bf16_f32 v54, v54, v55
	v_cvt_pk_bf16_f32 v55, v56, v57
	global_store_dwordx2 v18, v[54:55], s[60:61] offset:288
	s_add_u32 s62, s12, 0x48000
	s_addc_u32 s63, s13, 0
	s_waitcnt vmcnt(25)
	v_permlane16_swap_b32_e32 v224, v225
	s_nop 1
	v_permlane32_swap_b32_e32 v224, v225
	v_cvt_f32_ubyte1_e32 v155, v224
	v_cvt_f32_ubyte0_e32 v154, v224
	v_cvt_f32_ubyte3_e32 v157, v224
	v_cvt_f32_ubyte2_e32 v156, v224
	v_pk_mul_f32 v[154:155], v[154:155], s[14:15] op_sel_hi:[1,0]
	v_pk_mul_f32 v[156:157], v[156:157], s[14:15] op_sel_hi:[1,0]
	v_pk_mul_f32 v[50:51], v[50:51], v[154:155]
	v_pk_mul_f32 v[52:53], v[52:53], v[156:157]
	v_cvt_pk_bf16_f32 v50, v50, v51
	v_cvt_pk_bf16_f32 v51, v52, v53
	global_store_dwordx2 v18, v[50:51], s[62:63]
	v_cvt_f32_ubyte1_e32 v155, v225
	v_cvt_f32_ubyte0_e32 v154, v225
	v_cvt_f32_ubyte3_e32 v157, v225
	v_cvt_f32_ubyte2_e32 v156, v225
	v_pk_mul_f32 v[154:155], v[154:155], s[14:15] op_sel_hi:[1,0]
	v_pk_mul_f32 v[156:157], v[156:157], s[14:15] op_sel_hi:[1,0]
	v_pk_mul_f32 v[46:47], v[46:47], v[154:155]
	v_pk_mul_f32 v[48:49], v[48:49], v[156:157]
	v_cvt_pk_bf16_f32 v46, v46, v47
	v_cvt_pk_bf16_f32 v47, v48, v49
	global_store_dwordx2 v18, v[46:47], s[62:63] offset:32
	s_waitcnt vmcnt(26)
	v_permlane16_swap_b32_e32 v226, v227
	s_nop 1
	v_permlane32_swap_b32_e32 v226, v227
	v_cvt_f32_ubyte1_e32 v155, v226
	v_cvt_f32_ubyte0_e32 v154, v226
	v_cvt_f32_ubyte3_e32 v157, v226
	v_cvt_f32_ubyte2_e32 v156, v226
	v_pk_mul_f32 v[154:155], v[154:155], s[14:15] op_sel_hi:[1,0]
	v_pk_mul_f32 v[156:157], v[156:157], s[14:15] op_sel_hi:[1,0]
	v_pk_mul_f32 v[42:43], v[42:43], v[154:155]
	v_pk_mul_f32 v[44:45], v[44:45], v[156:157]
	v_cvt_pk_bf16_f32 v42, v42, v43
	v_cvt_pk_bf16_f32 v43, v44, v45
	global_store_dwordx2 v18, v[42:43], s[62:63] offset:256
	v_cvt_f32_ubyte1_e32 v155, v227
	v_cvt_f32_ubyte0_e32 v154, v227
	v_cvt_f32_ubyte3_e32 v157, v227
	v_cvt_f32_ubyte2_e32 v156, v227
	v_pk_mul_f32 v[154:155], v[154:155], s[14:15] op_sel_hi:[1,0]
	v_pk_mul_f32 v[156:157], v[156:157], s[14:15] op_sel_hi:[1,0]
	v_pk_mul_f32 v[38:39], v[38:39], v[154:155]
	v_pk_mul_f32 v[40:41], v[40:41], v[156:157]
	v_cvt_pk_bf16_f32 v38, v38, v39
	v_cvt_pk_bf16_f32 v39, v40, v41
	global_store_dwordx2 v18, v[38:39], s[62:63] offset:288
	s_add_u32 s60, s12, 0x50000
	s_addc_u32 s61, s13, 0
	s_waitcnt vmcnt(27)
	v_permlane16_swap_b32_e32 v228, v229
	s_nop 1
	v_permlane32_swap_b32_e32 v228, v229
	v_cvt_f32_ubyte1_e32 v155, v228
	v_cvt_f32_ubyte0_e32 v154, v228
	v_cvt_f32_ubyte3_e32 v157, v228
	v_cvt_f32_ubyte2_e32 v156, v228
	v_pk_mul_f32 v[154:155], v[154:155], s[14:15] op_sel_hi:[1,0]
	v_pk_mul_f32 v[156:157], v[156:157], s[14:15] op_sel_hi:[1,0]
	v_pk_mul_f32 v[34:35], v[34:35], v[154:155]
	v_pk_mul_f32 v[36:37], v[36:37], v[156:157]
	v_cvt_pk_bf16_f32 v34, v34, v35
	v_cvt_pk_bf16_f32 v35, v36, v37
	global_store_dwordx2 v18, v[34:35], s[60:61]
	v_cvt_f32_ubyte1_e32 v155, v229
	v_cvt_f32_ubyte0_e32 v154, v229
	v_cvt_f32_ubyte3_e32 v157, v229
	v_cvt_f32_ubyte2_e32 v156, v229
	v_pk_mul_f32 v[154:155], v[154:155], s[14:15] op_sel_hi:[1,0]
	v_pk_mul_f32 v[156:157], v[156:157], s[14:15] op_sel_hi:[1,0]
	v_pk_mul_f32 v[30:31], v[30:31], v[154:155]
	v_pk_mul_f32 v[32:33], v[32:33], v[156:157]
	v_cvt_pk_bf16_f32 v30, v30, v31
	v_cvt_pk_bf16_f32 v31, v32, v33
	global_store_dwordx2 v18, v[30:31], s[60:61] offset:32
	s_waitcnt vmcnt(28)
; DI bf16x4 pack4(float a, float b, float c, float d) { u32x2v u; u.x = pk2(a, b); u.y = pk2(c, d); return __builtin_bit_cast(bf16x4, u); }
; template <class Epi, class Sched>
; __device__ __forceinline__ void gemm_phase(PG8_LAS unsigned char* lds, const Gemm g, const Sched& S, const Epi& E) {
;     ...
;         if constexpr (!Epi::AFTER_DRAIN) { E(acc, cur, wr, wc, fr, fq); S.done(cur); }
;         if (!has_next) break;
; #pragma unroll
;         for (int a = 0; a < 2; ++a)
; #pragma unroll
;             for (int b = 0; b < 2; ++b)
; #pragma unroll
;                 for (int m = 0; m < 4; ++m)
; #pragma unroll
;                     for (int n = 0; n < 2; ++n) acc[a][b][m][n] = (f32x4){0.f, 0.f, 0.f, 0.f};
;         cur = nxt; cA = nA; cB = nB; ++ui;
;   DI void operator()(const f32x4 (&acc)[2][2][4][2], const pg8::Unit& u, int wr, int wc, int fr, int fq) const {
;     bf16_t* MERGED = (reinterpret_cast<bf16_t*>(p.ws + OFF_GA));
; #pragma unroll
;     for (int ai = 0; ai < 2; ++ai)
; #pragma unroll
;       for (int m = 0; m < 4; ++m) {
;         const int row = u.pm * 256 + 128 * ai + 64 * wr + 16 * m + fr;
; #pragma unroll
;         for (int bj = 0; bj < 2; ++bj)
; #pragma unroll
;           for (int n = 0; n < 2; ++n) {
;             const size_t idx = (size_t)row * 1024 + u.pn * 256 + 128 * bj + 32 * wc + 16 * n + 4 * fq;
;             const f32x4 a = acc[ai][bj][m][n];
;             if (MODE == 0) {
;               const unsigned g = *reinterpret_cast<const unsigned*>(reinterpret_cast<const unsigned char*>(p.ws + OFF_RB) + idx);
;               const float k = 1.f / 255.f;
;               st4(MERGED + idx, pack4((float)(g & 255u) * k * a[0], (float)((g >> 8) & 255u) * k * a[1], (float)((g >> 16) & 255u) * k * a[2], (float)(g >> 24) * k * a[3]));
	v_permlane16_swap_b32_e32 v230, v231
	s_nop 1
	v_permlane32_swap_b32_e32 v230, v231
	v_cvt_f32_ubyte1_e32 v155, v230
	v_cvt_f32_ubyte0_e32 v154, v230
	v_cvt_f32_ubyte3_e32 v157, v230
	v_cvt_f32_ubyte2_e32 v156, v230
	v_pk_mul_f32 v[154:155], v[154:155], s[14:15] op_sel_hi:[1,0]
	v_pk_mul_f32 v[156:157], v[156:157], s[14:15] op_sel_hi:[1,0]
	v_pk_mul_f32 v[26:27], v[26:27], v[154:155]
	v_pk_mul_f32 v[28:29], v[28:29], v[156:157]
	v_cvt_pk_bf16_f32 v26, v26, v27
	v_cvt_pk_bf16_f32 v27, v28, v29
	global_store_dwordx2 v18, v[26:27], s[60:61] offset:256
	v_cvt_f32_ubyte1_e32 v155, v231
	v_cvt_f32_ubyte0_e32 v154, v231
	v_cvt_f32_ubyte3_e32 v157, v231
	v_cvt_f32_ubyte2_e32 v156, v231
	v_pk_mul_f32 v[154:155], v[154:155], s[14:15] op_sel_hi:[1,0]
	v_pk_mul_f32 v[156:157], v[156:157], s[14:15] op_sel_hi:[1,0]
	v_pk_mul_f32 v[22:23], v[22:23], v[154:155]
	v_pk_mul_f32 v[24:25], v[24:25], v[156:157]
	v_cvt_pk_bf16_f32 v22, v22, v23
	v_cvt_pk_bf16_f32 v23, v24, v25
	global_store_dwordx2 v18, v[22:23], s[60:61] offset:288
	s_add_u32 s62, s12, 0x58000
	s_addc_u32 s63, s13, 0
	s_waitcnt vmcnt(29)
	v_permlane16_swap_b32_e32 v232, v233
	s_nop 1
	v_permlane32_swap_b32_e32 v232, v233
	v_cvt_f32_ubyte1_e32 v155, v232
	v_cvt_f32_ubyte0_e32 v154, v232
	v_cvt_f32_ubyte3_e32 v157, v232
	v_cvt_f32_ubyte2_e32 v156, v232
	v_pk_mul_f32 v[154:155], v[154:155], s[14:15] op_sel_hi:[1,0]
	v_pk_mul_f32 v[156:157], v[156:157], s[14:15] op_sel_hi:[1,0]
	v_pk_mul_f32 v[12:13], v[12:13], v[154:155]
	v_pk_mul_f32 v[14:15], v[14:15], v[156:157]
	v_cvt_pk_bf16_f32 v12, v12, v13
	v_cvt_pk_bf16_f32 v13, v14, v15
	global_store_dwordx2 v18, v[12:13], s[62:63]
	v_cvt_f32_ubyte1_e32 v155, v233
	v_cvt_f32_ubyte0_e32 v154, v233
	v_cvt_f32_ubyte3_e32 v157, v233
	v_cvt_f32_ubyte2_e32 v156, v233
	v_pk_mul_f32 v[154:155], v[154:155], s[14:15] op_sel_hi:[1,0]
	v_pk_mul_f32 v[156:157], v[156:157], s[14:15] op_sel_hi:[1,0]
	v_pk_mul_f32 v[8:9], v[8:9], v[154:155]
	v_pk_mul_f32 v[10:11], v[10:11], v[156:157]
	v_cvt_pk_bf16_f32 v8, v8, v9
	v_cvt_pk_bf16_f32 v9, v10, v11
	global_store_dwordx2 v18, v[8:9], s[62:63] offset:32
	s_waitcnt vmcnt(30)
	v_permlane16_swap_b32_e32 v234, v235
	s_nop 1
	v_permlane32_swap_b32_e32 v234, v235
	v_cvt_f32_ubyte1_e32 v155, v234
	v_cvt_f32_ubyte0_e32 v154, v234
	v_cvt_f32_ubyte3_e32 v157, v234
	v_cvt_f32_ubyte2_e32 v156, v234
	v_pk_mul_f32 v[154:155], v[154:155], s[14:15] op_sel_hi:[1,0]
	v_pk_mul_f32 v[156:157], v[156:157], s[14:15] op_sel_hi:[1,0]
	v_pk_mul_f32 v[4:5], v[4:5], v[154:155]
	v_pk_mul_f32 v[6:7], v[6:7], v[156:157]
	v_cvt_pk_bf16_f32 v4, v4, v5
	v_cvt_pk_bf16_f32 v5, v6, v7
	global_store_dwordx2 v18, v[4:5], s[62:63] offset:256
	v_cvt_f32_ubyte1_e32 v155, v235
	v_cvt_f32_ubyte0_e32 v154, v235
	v_cvt_f32_ubyte3_e32 v157, v235
	v_cvt_f32_ubyte2_e32 v156, v235
	v_pk_mul_f32 v[154:155], v[154:155], s[14:15] op_sel_hi:[1,0]
	v_pk_mul_f32 v[156:157], v[156:157], s[14:15] op_sel_hi:[1,0]
	v_pk_mul_f32 v[0:1], v[0:1], v[154:155]
	v_pk_mul_f32 v[2:3], v[2:3], v[156:157]
	v_cvt_pk_bf16_f32 v0, v0, v1
	v_cvt_pk_bf16_f32 v1, v2, v3
	global_store_dwordx2 v18, v[0:1], s[62:63] offset:288
	s_mov_b32 s11, s2
	s_mov_b32 s10, s4
	s_mov_b64 s[12:13], s[6:7]
	s_mov_b64 s[14:15], s[8:9]
	s_and_b64 vcc, exec, s[0:1]
	s_cbranch_vccnz .LBB0_2738

;   DI void mid(f32x4 (&acc)[2][2][4][2], const pg8::Unit& u, int wr, int wc, int fr, int fq) const {
; #pragma unroll
;     for (int ai = 0; ai < 2; ++ai)
; #pragma unroll
;       for (int m = 0; m < 4; ++m) {
;         int row = u.pm * 256 + 128 * ai + 64 * wr + 16 * m + fr;
;         asm volatile("" : "+v"(row));
; #pragma unroll
;         for (int bj = 0; bj < 2; ++bj)
; #pragma unroll
;           for (int n = 0; n < 2; ++n) {
;             const size_t idx = (size_t)row * 1024 + u.pn * 256 + 128 * bj + 32 * wc + 16 * n + 4 * fq;
;             const unsigned ga = *reinterpret_cast<const unsigned*>(reinterpret_cast<const unsigned char*>(p.ws + OFF_RA) + idx);
;             const unsigned gb = *reinterpret_cast<const unsigned*>(reinterpret_cast<const unsigned char*>(p.ws + OFF_RB) + idx);
; #pragma unroll
;             for (int j = 0; j < 4; ++j) {
;               const unsigned a8 = (ga >> (8 * j)) & 255u, b8 = (gb >> (8 * j)) & 255u;
;               acc[ai][bj][m][n][j] *= (float)a8 * __builtin_amdgcn_rcpf((float)(b8 > 1u ? b8 : 1u));
;             }
;           }
.LBB0_2736:
	s_cmpk_lg_i32 s14, 0x400
	s_cbranch_scc1 .LBB0_2735
	v_lshl_add_u32 v16, v148, 10, v150
	v_add_u32_e32 v16, v16, v138
	s_add_u32 s56, s46, 0x0
	s_addc_u32 s57, s47, 0
	s_add_u32 s58, s48, 0x0
	s_addc_u32 s59, s49, 0
	global_load_dwordx2 v[186:187], v16, s[56:57]
	global_load_dwordx2 v[188:189], v16, s[58:59]
	global_load_dwordx2 v[190:191], v16, s[56:57] offset:128
	global_load_dwordx2 v[192:193], v16, s[58:59] offset:128
	s_add_u32 s60, s46, 0x4000
	s_addc_u32 s61, s47, 0
	s_add_u32 s62, s48, 0x4000
	s_addc_u32 s63, s49, 0
	global_load_dwordx2 v[194:195], v16, s[60:61]
	global_load_dwordx2 v[196:197], v16, s[62:63]
	global_load_dwordx2 v[198:199], v16, s[60:61] offset:128
	global_load_dwordx2 v[200:201], v16, s[62:63] offset:128
	s_add_u32 s56, s46, 0x8000
	s_addc_u32 s57, s47, 0
	s_add_u32 s58, s48, 0x8000
	s_addc_u32 s59, s49, 0
	global_load_dwordx2 v[202:203], v16, s[56:57]
	global_load_dwordx2 v[204:205], v16, s[58:59]
	global_load_dwordx2 v[206:207], v16, s[56:57] offset:128
	global_load_dwordx2 v[208:209], v16, s[58:59] offset:128
	s_add_u32 s60, s46, 0xc000
	s_addc_u32 s61, s47, 0
	s_add_u32 s62, s48, 0xc000
	s_addc_u32 s63, s49, 0
	global_load_dwordx2 v[210:211], v16, s[60:61]
	global_load_dwordx2 v[212:213], v16, s[62:63]
	global_load_dwordx2 v[214:215], v16, s[60:61] offset:128
	global_load_dwordx2 v[216:217], v16, s[62:63] offset:128
	s_add_u32 s56, s46, 0x20000
	s_addc_u32 s57, s47, 0
	s_add_u32 s58, s48, 0x20000
	s_addc_u32 s59, s49, 0
	global_load_dwordx2 v[218:219], v16, s[56:57]
	global_load_dwordx2 v[220:221], v16, s[58:59]
	global_load_dwordx2 v[222:223], v16, s[56:57] offset:128
	global_load_dwordx2 v[224:225], v16, s[58:59] offset:128
	s_add_u32 s60, s46, 0x24000
	s_addc_u32 s61, s47, 0
	s_add_u32 s62, s48, 0x24000
	s_addc_u32 s63, s49, 0
	global_load_dwordx2 v[226:227], v16, s[60:61]
	global_load_dwordx2 v[228:229], v16, s[62:63]
	global_load_dwordx2 v[230:231], v16, s[60:61] offset:128
	global_load_dwordx2 v[232:233], v16, s[62:63] offset:128
	s_waitcnt vmcnt(22)
	v_permlane16_swap_b32_e32 v186, v187
	v_permlane16_swap_b32_e32 v188, v189
	s_nop 0
	v_permlane32_swap_b32_e32 v186, v187
	v_permlane32_swap_b32_e32 v188, v189
	v_max_u32_sdwa v154, v188, v182 dst_sel:DWORD dst_unused:UNUSED_PAD src0_sel:BYTE_0 src1_sel:DWORD
	v_max_u32_sdwa v155, v188, v182 dst_sel:DWORD dst_unused:UNUSED_PAD src0_sel:BYTE_1 src1_sel:DWORD
	v_max_u32_sdwa v156, v188, v182 dst_sel:DWORD dst_unused:UNUSED_PAD src0_sel:BYTE_2 src1_sel:DWORD
	v_max_u32_sdwa v157, v188, v182 dst_sel:DWORD dst_unused:UNUSED_PAD src0_sel:BYTE_3 src1_sel:DWORD
	v_cvt_f32_ubyte0_e32 v154, v154
	v_cvt_f32_ubyte0_e32 v155, v155
	v_cvt_f32_ubyte0_e32 v156, v156
	v_cvt_f32_ubyte0_e32 v157, v157
	v_rcp_iflag_f32_e32 v154, v154
	v_rcp_iflag_f32_e32 v155, v155
	v_rcp_iflag_f32_e32 v156, v156
	v_rcp_iflag_f32_e32 v157, v157
	v_cvt_f32_ubyte0_e32 v178, v186
	v_cvt_f32_ubyte1_e32 v179, v186
	v_cvt_f32_ubyte2_e32 v180, v186
	v_cvt_f32_ubyte3_e32 v181, v186
	v_pk_mul_f32 v[154:155], v[154:155], v[178:179]
	v_pk_mul_f32 v[156:157], v[156:157], v[180:181]
	v_pk_mul_f32 v[130:131], v[130:131], v[154:155]
	v_pk_mul_f32 v[132:133], v[132:133], v[156:157]
	v_max_u32_sdwa v154, v189, v182 dst_sel:DWORD dst_unused:UNUSED_PAD src0_sel:BYTE_0 src1_sel:DWORD
	v_max_u32_sdwa v155, v189, v182 dst_sel:DWORD dst_unused:UNUSED_PAD src0_sel:BYTE_1 src1_sel:DWORD
	v_max_u32_sdwa v156, v189, v182 dst_sel:DWORD dst_unused:UNUSED_PAD src0_sel:BYTE_2 src1_sel:DWORD
	v_max_u32_sdwa v157, v189, v182 dst_sel:DWORD dst_unused:UNUSED_PAD src0_sel:BYTE_3 src1_sel:DWORD
	v_cvt_f32_ubyte0_e32 v154, v154
	v_cvt_f32_ubyte0_e32 v155, v155
	v_cvt_f32_ubyte0_e32 v156, v156
	v_cvt_f32_ubyte0_e32 v157, v157
	v_rcp_iflag_f32_e32 v154, v154
	v_rcp_iflag_f32_e32 v155, v155
	v_rcp_iflag_f32_e32 v156, v156
	v_rcp_iflag_f32_e32 v157, v157
	v_cvt_f32_ubyte0_e32 v178, v187
	v_cvt_f32_ubyte1_e32 v179, v187
	v_cvt_f32_ubyte2_e32 v180, v187
	v_cvt_f32_ubyte3_e32 v181, v187
	s_add_u32 s56, s46, 0x28000
	s_addc_u32 s57, s47, 0
	s_add_u32 s58, s48, 0x28000
	s_addc_u32 s59, s49, 0
	global_load_dwordx2 v[186:187], v16, s[56:57]
	global_load_dwordx2 v[188:189], v16, s[58:59]
	v_pk_mul_f32 v[154:155], v[154:155], v[178:179]
	v_pk_mul_f32 v[156:157], v[156:157], v[180:181]
	v_pk_mul_f32 v[126:127], v[126:127], v[154:155]
	v_pk_mul_f32 v[128:129], v[128:129], v[156:157]
	s_waitcnt vmcnt(22)
	v_permlane16_swap_b32_e32 v190, v191
	v_permlane16_swap_b32_e32 v192, v193
	s_nop 0
	v_permlane32_swap_b32_e32 v190, v191
	v_permlane32_swap_b32_e32 v192, v193
	v_max_u32_sdwa v154, v192, v182 dst_sel:DWORD dst_unused:UNUSED_PAD src0_sel:BYTE_0 src1_sel:DWORD
	v_max_u32_sdwa v155, v192, v182 dst_sel:DWORD dst_unused:UNUSED_PAD src0_sel:BYTE_1 src1_sel:DWORD
	v_max_u32_sdwa v156, v192, v182 dst_sel:DWORD dst_unused:UNUSED_PAD src0_sel:BYTE_2 src1_sel:DWORD
	v_max_u32_sdwa v157, v192, v182 dst_sel:DWORD dst_unused:UNUSED_PAD src0_sel:BYTE_3 src1_sel:DWORD
	v_cvt_f32_ubyte0_e32 v154, v154
	v_cvt_f32_ubyte0_e32 v155, v155
	v_cvt_f32_ubyte0_e32 v156, v156
	v_cvt_f32_ubyte0_e32 v157, v157
	v_rcp_iflag_f32_e32 v154, v154
	v_rcp_iflag_f32_e32 v155, v155
	v_rcp_iflag_f32_e32 v156, v156
	v_rcp_iflag_f32_e32 v157, v157
	v_cvt_f32_ubyte0_e32 v178, v190
	v_cvt_f32_ubyte1_e32 v179, v190
	v_cvt_f32_ubyte2_e32 v180, v190
	v_cvt_f32_ubyte3_e32 v181, v190
	v_pk_mul_f32 v[154:155], v[154:155], v[178:179]
	v_pk_mul_f32 v[156:157], v[156:157], v[180:181]
	v_pk_mul_f32 v[122:123], v[122:123], v[154:155]
	v_pk_mul_f32 v[124:125], v[124:125], v[156:157]
	v_max_u32_sdwa v154, v193, v182 dst_sel:DWORD dst_unused:UNUSED_PAD src0_sel:BYTE_0 src1_sel:DWORD
	v_max_u32_sdwa v155, v193, v182 dst_sel:DWORD dst_unused:UNUSED_PAD src0_sel:BYTE_1 src1_sel:DWORD
	v_max_u32_sdwa v156, v193, v182 dst_sel:DWORD dst_unused:UNUSED_PAD src0_sel:BYTE_2 src1_sel:DWORD
	v_max_u32_sdwa v157, v193, v182 dst_sel:DWORD dst_unused:UNUSED_PAD src0_sel:BYTE_3 src1_sel:DWORD
	v_cvt_f32_ubyte0_e32 v154, v154
	v_cvt_f32_ubyte0_e32 v155, v155
	v_cvt_f32_ubyte0_e32 v156, v156
	v_cvt_f32_ubyte0_e32 v157, v157
	v_rcp_iflag_f32_e32 v154, v154
	v_rcp_iflag_f32_e32 v155, v155
	v_rcp_iflag_f32_e32 v156, v156
	v_rcp_iflag_f32_e32 v157, v157
	v_cvt_f32_ubyte0_e32 v178, v191
	v_cvt_f32_ubyte1_e32 v179, v191
	v_cvt_f32_ubyte2_e32 v180, v191
	v_cvt_f32_ubyte3_e32 v181, v191
	global_load_dwordx2 v[190:191], v16, s[56:57] offset:128
	global_load_dwordx2 v[192:193], v16, s[58:59] offset:128
	v_pk_mul_f32 v[154:155], v[154:155], v[178:179]
	v_pk_mul_f32 v[156:157], v[156:157], v[180:181]
	v_pk_mul_f32 v[118:119], v[118:119], v[154:155]
	v_pk_mul_f32 v[120:121], v[120:121], v[156:157]
	s_waitcnt vmcnt(22)
;   DI void mid(f32x4 (&acc)[2][2][4][2], const pg8::Unit& u, int wr, int wc, int fr, int fq) const {
; #pragma unroll
;     for (int ai = 0; ai < 2; ++ai)
; #pragma unroll
;       for (int m = 0; m < 4; ++m) {
;         int row = u.pm * 256 + 128 * ai + 64 * wr + 16 * m + fr;
;         asm volatile("" : "+v"(row));
; #pragma unroll
;         for (int bj = 0; bj < 2; ++bj)
; #pragma unroll
;           for (int n = 0; n < 2; ++n) {
;             const size_t idx = (size_t)row * 1024 + u.pn * 256 + 128 * bj + 32 * wc + 16 * n + 4 * fq;
;             const unsigned ga = *reinterpret_cast<const unsigned*>(reinterpret_cast<const unsigned char*>(p.ws + OFF_RA) + idx);
;             const unsigned gb = *reinterpret_cast<const unsigned*>(reinterpret_cast<const unsigned char*>(p.ws + OFF_RB) + idx);
; #pragma unroll
;             for (int j = 0; j < 4; ++j) {
;               const unsigned a8 = (ga >> (8 * j)) & 255u, b8 = (gb >> (8 * j)) & 255u;
;               acc[ai][bj][m][n][j] *= (float)a8 * __builtin_amdgcn_rcpf((float)(b8 > 1u ? b8 : 1u));
;             }
;           }
	v_permlane16_swap_b32_e32 v194, v195
	v_permlane16_swap_b32_e32 v196, v197
	s_nop 0
	v_permlane32_swap_b32_e32 v194, v195
	v_permlane32_swap_b32_e32 v196, v197
	v_max_u32_sdwa v154, v196, v182 dst_sel:DWORD dst_unused:UNUSED_PAD src0_sel:BYTE_0 src1_sel:DWORD
	v_max_u32_sdwa v155, v196, v182 dst_sel:DWORD dst_unused:UNUSED_PAD src0_sel:BYTE_1 src1_sel:DWORD
	v_max_u32_sdwa v156, v196, v182 dst_sel:DWORD dst_unused:UNUSED_PAD src0_sel:BYTE_2 src1_sel:DWORD
	v_max_u32_sdwa v157, v196, v182 dst_sel:DWORD dst_unused:UNUSED_PAD src0_sel:BYTE_3 src1_sel:DWORD
	v_cvt_f32_ubyte0_e32 v154, v154
	v_cvt_f32_ubyte0_e32 v155, v155
	v_cvt_f32_ubyte0_e32 v156, v156
	v_cvt_f32_ubyte0_e32 v157, v157
	v_rcp_iflag_f32_e32 v154, v154
	v_rcp_iflag_f32_e32 v155, v155
	v_rcp_iflag_f32_e32 v156, v156
	v_rcp_iflag_f32_e32 v157, v157
	v_cvt_f32_ubyte0_e32 v178, v194
	v_cvt_f32_ubyte1_e32 v179, v194
	v_cvt_f32_ubyte2_e32 v180, v194
	v_cvt_f32_ubyte3_e32 v181, v194
	v_pk_mul_f32 v[154:155], v[154:155], v[178:179]
	v_pk_mul_f32 v[156:157], v[156:157], v[180:181]
	v_pk_mul_f32 v[114:115], v[114:115], v[154:155]
	v_pk_mul_f32 v[116:117], v[116:117], v[156:157]
	v_max_u32_sdwa v154, v197, v182 dst_sel:DWORD dst_unused:UNUSED_PAD src0_sel:BYTE_0 src1_sel:DWORD
	v_max_u32_sdwa v155, v197, v182 dst_sel:DWORD dst_unused:UNUSED_PAD src0_sel:BYTE_1 src1_sel:DWORD
	v_max_u32_sdwa v156, v197, v182 dst_sel:DWORD dst_unused:UNUSED_PAD src0_sel:BYTE_2 src1_sel:DWORD
	v_max_u32_sdwa v157, v197, v182 dst_sel:DWORD dst_unused:UNUSED_PAD src0_sel:BYTE_3 src1_sel:DWORD
	v_cvt_f32_ubyte0_e32 v154, v154
	v_cvt_f32_ubyte0_e32 v155, v155
	v_cvt_f32_ubyte0_e32 v156, v156
	v_cvt_f32_ubyte0_e32 v157, v157
	v_rcp_iflag_f32_e32 v154, v154
	v_rcp_iflag_f32_e32 v155, v155
	v_rcp_iflag_f32_e32 v156, v156
	v_rcp_iflag_f32_e32 v157, v157
	v_cvt_f32_ubyte0_e32 v178, v195
	v_cvt_f32_ubyte1_e32 v179, v195
	v_cvt_f32_ubyte2_e32 v180, v195
	v_cvt_f32_ubyte3_e32 v181, v195
	s_add_u32 s60, s46, 0x2c000
	s_addc_u32 s61, s47, 0
	s_add_u32 s62, s48, 0x2c000
	s_addc_u32 s63, s49, 0
	global_load_dwordx2 v[194:195], v16, s[60:61]
	global_load_dwordx2 v[196:197], v16, s[62:63]
	v_pk_mul_f32 v[154:155], v[154:155], v[178:179]
	v_pk_mul_f32 v[156:157], v[156:157], v[180:181]
	v_pk_mul_f32 v[110:111], v[110:111], v[154:155]
	v_pk_mul_f32 v[112:113], v[112:113], v[156:157]
	s_waitcnt vmcnt(22)
	v_permlane16_swap_b32_e32 v198, v199
	v_permlane16_swap_b32_e32 v200, v201
	s_nop 0
	v_permlane32_swap_b32_e32 v198, v199
	v_permlane32_swap_b32_e32 v200, v201
	v_max_u32_sdwa v154, v200, v182 dst_sel:DWORD dst_unused:UNUSED_PAD src0_sel:BYTE_0 src1_sel:DWORD
	v_max_u32_sdwa v155, v200, v182 dst_sel:DWORD dst_unused:UNUSED_PAD src0_sel:BYTE_1 src1_sel:DWORD
	v_max_u32_sdwa v156, v200, v182 dst_sel:DWORD dst_unused:UNUSED_PAD src0_sel:BYTE_2 src1_sel:DWORD
	v_max_u32_sdwa v157, v200, v182 dst_sel:DWORD dst_unused:UNUSED_PAD src0_sel:BYTE_3 src1_sel:DWORD
	v_cvt_f32_ubyte0_e32 v154, v154
	v_cvt_f32_ubyte0_e32 v155, v155
	v_cvt_f32_ubyte0_e32 v156, v156
	v_cvt_f32_ubyte0_e32 v157, v157
	v_rcp_iflag_f32_e32 v154, v154
	v_rcp_iflag_f32_e32 v155, v155
	v_rcp_iflag_f32_e32 v156, v156
	v_rcp_iflag_f32_e32 v157, v157
	v_cvt_f32_ubyte0_e32 v178, v198
	v_cvt_f32_ubyte1_e32 v179, v198
	v_cvt_f32_ubyte2_e32 v180, v198
	v_cvt_f32_ubyte3_e32 v181, v198
	v_pk_mul_f32 v[154:155], v[154:155], v[178:179]
	v_pk_mul_f32 v[156:157], v[156:157], v[180:181]
	v_pk_mul_f32 v[106:107], v[106:107], v[154:155]
	v_pk_mul_f32 v[108:109], v[108:109], v[156:157]
	v_max_u32_sdwa v154, v201, v182 dst_sel:DWORD dst_unused:UNUSED_PAD src0_sel:BYTE_0 src1_sel:DWORD
	v_max_u32_sdwa v155, v201, v182 dst_sel:DWORD dst_unused:UNUSED_PAD src0_sel:BYTE_1 src1_sel:DWORD
	v_max_u32_sdwa v156, v201, v182 dst_sel:DWORD dst_unused:UNUSED_PAD src0_sel:BYTE_2 src1_sel:DWORD
	v_max_u32_sdwa v157, v201, v182 dst_sel:DWORD dst_unused:UNUSED_PAD src0_sel:BYTE_3 src1_sel:DWORD
	v_cvt_f32_ubyte0_e32 v154, v154
	v_cvt_f32_ubyte0_e32 v155, v155
	v_cvt_f32_ubyte0_e32 v156, v156
	v_cvt_f32_ubyte0_e32 v157, v157
	v_rcp_iflag_f32_e32 v154, v154
	v_rcp_iflag_f32_e32 v155, v155
	v_rcp_iflag_f32_e32 v156, v156
	v_rcp_iflag_f32_e32 v157, v157
	v_cvt_f32_ubyte0_e32 v178, v199
	v_cvt_f32_ubyte1_e32 v179, v199
	v_cvt_f32_ubyte2_e32 v180, v199
	v_cvt_f32_ubyte3_e32 v181, v199
	global_load_dwordx2 v[198:199], v16, s[60:61] offset:128
	global_load_dwordx2 v[200:201], v16, s[62:63] offset:128
	v_pk_mul_f32 v[154:155], v[154:155], v[178:179]
	v_pk_mul_f32 v[156:157], v[156:157], v[180:181]
	v_pk_mul_f32 v[102:103], v[102:103], v[154:155]
	v_pk_mul_f32 v[104:105], v[104:105], v[156:157]
	s_waitcnt vmcnt(22)
;   DI void mid(f32x4 (&acc)[2][2][4][2], const pg8::Unit& u, int wr, int wc, int fr, int fq) const {
; #pragma unroll
;     for (int ai = 0; ai < 2; ++ai)
; #pragma unroll
;       for (int m = 0; m < 4; ++m) {
;         int row = u.pm * 256 + 128 * ai + 64 * wr + 16 * m + fr;
;         asm volatile("" : "+v"(row));
; #pragma unroll
;         for (int bj = 0; bj < 2; ++bj)
; #pragma unroll
;           for (int n = 0; n < 2; ++n) {
;             const size_t idx = (size_t)row * 1024 + u.pn * 256 + 128 * bj + 32 * wc + 16 * n + 4 * fq;
;             const unsigned ga = *reinterpret_cast<const unsigned*>(reinterpret_cast<const unsigned char*>(p.ws + OFF_RA) + idx);
;             const unsigned gb = *reinterpret_cast<const unsigned*>(reinterpret_cast<const unsigned char*>(p.ws + OFF_RB) + idx);
; #pragma unroll
;             for (int j = 0; j < 4; ++j) {
;               const unsigned a8 = (ga >> (8 * j)) & 255u, b8 = (gb >> (8 * j)) & 255u;
;               acc[ai][bj][m][n][j] *= (float)a8 * __builtin_amdgcn_rcpf((float)(b8 > 1u ? b8 : 1u));
;             }
;           }
	v_permlane16_swap_b32_e32 v202, v203
	v_permlane16_swap_b32_e32 v204, v205
	s_nop 0
	v_permlane32_swap_b32_e32 v202, v203
	v_permlane32_swap_b32_e32 v204, v205
	v_max_u32_sdwa v154, v204, v182 dst_sel:DWORD dst_unused:UNUSED_PAD src0_sel:BYTE_0 src1_sel:DWORD
	v_max_u32_sdwa v155, v204, v182 dst_sel:DWORD dst_unused:UNUSED_PAD src0_sel:BYTE_1 src1_sel:DWORD
	v_max_u32_sdwa v156, v204, v182 dst_sel:DWORD dst_unused:UNUSED_PAD src0_sel:BYTE_2 src1_sel:DWORD
	v_max_u32_sdwa v157, v204, v182 dst_sel:DWORD dst_unused:UNUSED_PAD src0_sel:BYTE_3 src1_sel:DWORD
	v_cvt_f32_ubyte0_e32 v154, v154
	v_cvt_f32_ubyte0_e32 v155, v155
	v_cvt_f32_ubyte0_e32 v156, v156
	v_cvt_f32_ubyte0_e32 v157, v157
	v_rcp_iflag_f32_e32 v154, v154
	v_rcp_iflag_f32_e32 v155, v155
	v_rcp_iflag_f32_e32 v156, v156
	v_rcp_iflag_f32_e32 v157, v157
	v_cvt_f32_ubyte0_e32 v178, v202
	v_cvt_f32_ubyte1_e32 v179, v202
	v_cvt_f32_ubyte2_e32 v180, v202
	v_cvt_f32_ubyte3_e32 v181, v202
	v_pk_mul_f32 v[154:155], v[154:155], v[178:179]
	v_pk_mul_f32 v[156:157], v[156:157], v[180:181]
	v_pk_mul_f32 v[98:99], v[98:99], v[154:155]
	v_pk_mul_f32 v[100:101], v[100:101], v[156:157]
	v_max_u32_sdwa v154, v205, v182 dst_sel:DWORD dst_unused:UNUSED_PAD src0_sel:BYTE_0 src1_sel:DWORD
	v_max_u32_sdwa v155, v205, v182 dst_sel:DWORD dst_unused:UNUSED_PAD src0_sel:BYTE_1 src1_sel:DWORD
	v_max_u32_sdwa v156, v205, v182 dst_sel:DWORD dst_unused:UNUSED_PAD src0_sel:BYTE_2 src1_sel:DWORD
	v_max_u32_sdwa v157, v205, v182 dst_sel:DWORD dst_unused:UNUSED_PAD src0_sel:BYTE_3 src1_sel:DWORD
	v_cvt_f32_ubyte0_e32 v154, v154
	v_cvt_f32_ubyte0_e32 v155, v155
	v_cvt_f32_ubyte0_e32 v156, v156
	v_cvt_f32_ubyte0_e32 v157, v157
	v_rcp_iflag_f32_e32 v154, v154
	v_rcp_iflag_f32_e32 v155, v155
	v_rcp_iflag_f32_e32 v156, v156
	v_rcp_iflag_f32_e32 v157, v157
	v_cvt_f32_ubyte0_e32 v178, v203
	v_cvt_f32_ubyte1_e32 v179, v203
	v_cvt_f32_ubyte2_e32 v180, v203
	v_cvt_f32_ubyte3_e32 v181, v203
	v_pk_mul_f32 v[154:155], v[154:155], v[178:179]
	v_pk_mul_f32 v[156:157], v[156:157], v[180:181]
	v_pk_mul_f32 v[94:95], v[94:95], v[154:155]
	v_pk_mul_f32 v[96:97], v[96:97], v[156:157]
	s_waitcnt vmcnt(20)
	v_permlane16_swap_b32_e32 v206, v207
	v_permlane16_swap_b32_e32 v208, v209
	s_nop 0
	v_permlane32_swap_b32_e32 v206, v207
	v_permlane32_swap_b32_e32 v208, v209
	v_max_u32_sdwa v154, v208, v182 dst_sel:DWORD dst_unused:UNUSED_PAD src0_sel:BYTE_0 src1_sel:DWORD
	v_max_u32_sdwa v155, v208, v182 dst_sel:DWORD dst_unused:UNUSED_PAD src0_sel:BYTE_1 src1_sel:DWORD
	v_max_u32_sdwa v156, v208, v182 dst_sel:DWORD dst_unused:UNUSED_PAD src0_sel:BYTE_2 src1_sel:DWORD
	v_max_u32_sdwa v157, v208, v182 dst_sel:DWORD dst_unused:UNUSED_PAD src0_sel:BYTE_3 src1_sel:DWORD
	v_cvt_f32_ubyte0_e32 v154, v154
	v_cvt_f32_ubyte0_e32 v155, v155
	v_cvt_f32_ubyte0_e32 v156, v156
	v_cvt_f32_ubyte0_e32 v157, v157
	v_rcp_iflag_f32_e32 v154, v154
	v_rcp_iflag_f32_e32 v155, v155
	v_rcp_iflag_f32_e32 v156, v156
	v_rcp_iflag_f32_e32 v157, v157
	v_cvt_f32_ubyte0_e32 v178, v206
	v_cvt_f32_ubyte1_e32 v179, v206
	v_cvt_f32_ubyte2_e32 v180, v206
	v_cvt_f32_ubyte3_e32 v181, v206
	v_pk_mul_f32 v[154:155], v[154:155], v[178:179]
	v_pk_mul_f32 v[156:157], v[156:157], v[180:181]
	v_pk_mul_f32 v[90:91], v[90:91], v[154:155]
	v_pk_mul_f32 v[92:93], v[92:93], v[156:157]
	v_max_u32_sdwa v154, v209, v182 dst_sel:DWORD dst_unused:UNUSED_PAD src0_sel:BYTE_0 src1_sel:DWORD
	v_max_u32_sdwa v155, v209, v182 dst_sel:DWORD dst_unused:UNUSED_PAD src0_sel:BYTE_1 src1_sel:DWORD
	v_max_u32_sdwa v156, v209, v182 dst_sel:DWORD dst_unused:UNUSED_PAD src0_sel:BYTE_2 src1_sel:DWORD
	v_max_u32_sdwa v157, v209, v182 dst_sel:DWORD dst_unused:UNUSED_PAD src0_sel:BYTE_3 src1_sel:DWORD
	v_cvt_f32_ubyte0_e32 v154, v154
	v_cvt_f32_ubyte0_e32 v155, v155
	v_cvt_f32_ubyte0_e32 v156, v156
	v_cvt_f32_ubyte0_e32 v157, v157
	v_rcp_iflag_f32_e32 v154, v154
	v_rcp_iflag_f32_e32 v155, v155
	v_rcp_iflag_f32_e32 v156, v156
	v_rcp_iflag_f32_e32 v157, v157
	v_cvt_f32_ubyte0_e32 v178, v207
	v_cvt_f32_ubyte1_e32 v179, v207
	v_cvt_f32_ubyte2_e32 v180, v207
	v_cvt_f32_ubyte3_e32 v181, v207
	v_pk_mul_f32 v[154:155], v[154:155], v[178:179]
	v_pk_mul_f32 v[156:157], v[156:157], v[180:181]
	v_pk_mul_f32 v[86:87], v[86:87], v[154:155]
	v_pk_mul_f32 v[88:89], v[88:89], v[156:157]
	s_waitcnt vmcnt(18)
	v_permlane16_swap_b32_e32 v210, v211
	v_permlane16_swap_b32_e32 v212, v213
	s_nop 0
	v_permlane32_swap_b32_e32 v210, v211
	v_permlane32_swap_b32_e32 v212, v213
	v_max_u32_sdwa v154, v212, v182 dst_sel:DWORD dst_unused:UNUSED_PAD src0_sel:BYTE_0 src1_sel:DWORD
	v_max_u32_sdwa v155, v212, v182 dst_sel:DWORD dst_unused:UNUSED_PAD src0_sel:BYTE_1 src1_sel:DWORD
	v_max_u32_sdwa v156, v212, v182 dst_sel:DWORD dst_unused:UNUSED_PAD src0_sel:BYTE_2 src1_sel:DWORD
	v_max_u32_sdwa v157, v212, v182 dst_sel:DWORD dst_unused:UNUSED_PAD src0_sel:BYTE_3 src1_sel:DWORD
	v_cvt_f32_ubyte0_e32 v154, v154
	v_cvt_f32_ubyte0_e32 v155, v155
	v_cvt_f32_ubyte0_e32 v156, v156
	v_cvt_f32_ubyte0_e32 v157, v157
	v_rcp_iflag_f32_e32 v154, v154
	v_rcp_iflag_f32_e32 v155, v155
	v_rcp_iflag_f32_e32 v156, v156
	v_rcp_iflag_f32_e32 v157, v157
	v_cvt_f32_ubyte0_e32 v178, v210
	v_cvt_f32_ubyte1_e32 v179, v210
	v_cvt_f32_ubyte2_e32 v180, v210
	v_cvt_f32_ubyte3_e32 v181, v210
	v_pk_mul_f32 v[154:155], v[154:155], v[178:179]
	v_pk_mul_f32 v[156:157], v[156:157], v[180:181]
	v_pk_mul_f32 v[82:83], v[82:83], v[154:155]
	v_pk_mul_f32 v[84:85], v[84:85], v[156:157]
	v_max_u32_sdwa v154, v213, v182 dst_sel:DWORD dst_unused:UNUSED_PAD src0_sel:BYTE_0 src1_sel:DWORD
	v_max_u32_sdwa v155, v213, v182 dst_sel:DWORD dst_unused:UNUSED_PAD src0_sel:BYTE_1 src1_sel:DWORD
	v_max_u32_sdwa v156, v213, v182 dst_sel:DWORD dst_unused:UNUSED_PAD src0_sel:BYTE_2 src1_sel:DWORD
	v_max_u32_sdwa v157, v213, v182 dst_sel:DWORD dst_unused:UNUSED_PAD src0_sel:BYTE_3 src1_sel:DWORD
	v_cvt_f32_ubyte0_e32 v154, v154
	v_cvt_f32_ubyte0_e32 v155, v155
	v_cvt_f32_ubyte0_e32 v156, v156
	v_cvt_f32_ubyte0_e32 v157, v157
	v_rcp_iflag_f32_e32 v154, v154
	v_rcp_iflag_f32_e32 v155, v155
	v_rcp_iflag_f32_e32 v156, v156
	v_rcp_iflag_f32_e32 v157, v157
	v_cvt_f32_ubyte0_e32 v178, v211
	v_cvt_f32_ubyte1_e32 v179, v211
	v_cvt_f32_ubyte2_e32 v180, v211
	v_cvt_f32_ubyte3_e32 v181, v211
	v_pk_mul_f32 v[154:155], v[154:155], v[178:179]
	v_pk_mul_f32 v[156:157], v[156:157], v[180:181]
	v_pk_mul_f32 v[78:79], v[78:79], v[154:155]
	v_pk_mul_f32 v[80:81], v[80:81], v[156:157]
	s_waitcnt vmcnt(16)
;   DI void mid(f32x4 (&acc)[2][2][4][2], const pg8::Unit& u, int wr, int wc, int fr, int fq) const {
; #pragma unroll
;     for (int ai = 0; ai < 2; ++ai)
; #pragma unroll
;       for (int m = 0; m < 4; ++m) {
;         int row = u.pm * 256 + 128 * ai + 64 * wr + 16 * m + fr;
;         asm volatile("" : "+v"(row));
; #pragma unroll
;         for (int bj = 0; bj < 2; ++bj)
; #pragma unroll
;           for (int n = 0; n < 2; ++n) {
;             const size_t idx = (size_t)row * 1024 + u.pn * 256 + 128 * bj + 32 * wc + 16 * n + 4 * fq;
;             const unsigned ga = *reinterpret_cast<const unsigned*>(reinterpret_cast<const unsigned char*>(p.ws + OFF_RA) + idx);
;             const unsigned gb = *reinterpret_cast<const unsigned*>(reinterpret_cast<const unsigned char*>(p.ws + OFF_RB) + idx);
; #pragma unroll
;             for (int j = 0; j < 4; ++j) {
;               const unsigned a8 = (ga >> (8 * j)) & 255u, b8 = (gb >> (8 * j)) & 255u;
;               acc[ai][bj][m][n][j] *= (float)a8 * __builtin_amdgcn_rcpf((float)(b8 > 1u ? b8 : 1u));
;             }
;           }
	v_permlane16_swap_b32_e32 v214, v215
	v_permlane16_swap_b32_e32 v216, v217
	s_nop 0
	v_permlane32_swap_b32_e32 v214, v215
	v_permlane32_swap_b32_e32 v216, v217
	v_max_u32_sdwa v154, v216, v182 dst_sel:DWORD dst_unused:UNUSED_PAD src0_sel:BYTE_0 src1_sel:DWORD
	v_max_u32_sdwa v155, v216, v182 dst_sel:DWORD dst_unused:UNUSED_PAD src0_sel:BYTE_1 src1_sel:DWORD
	v_max_u32_sdwa v156, v216, v182 dst_sel:DWORD dst_unused:UNUSED_PAD src0_sel:BYTE_2 src1_sel:DWORD
	v_max_u32_sdwa v157, v216, v182 dst_sel:DWORD dst_unused:UNUSED_PAD src0_sel:BYTE_3 src1_sel:DWORD
	v_cvt_f32_ubyte0_e32 v154, v154
	v_cvt_f32_ubyte0_e32 v155, v155
	v_cvt_f32_ubyte0_e32 v156, v156
	v_cvt_f32_ubyte0_e32 v157, v157
	v_rcp_iflag_f32_e32 v154, v154
	v_rcp_iflag_f32_e32 v155, v155
	v_rcp_iflag_f32_e32 v156, v156
	v_rcp_iflag_f32_e32 v157, v157
	v_cvt_f32_ubyte0_e32 v178, v214
	v_cvt_f32_ubyte1_e32 v179, v214
	v_cvt_f32_ubyte2_e32 v180, v214
	v_cvt_f32_ubyte3_e32 v181, v214
	v_pk_mul_f32 v[154:155], v[154:155], v[178:179]
	v_pk_mul_f32 v[156:157], v[156:157], v[180:181]
	v_pk_mul_f32 v[74:75], v[74:75], v[154:155]
	v_pk_mul_f32 v[76:77], v[76:77], v[156:157]
	v_max_u32_sdwa v154, v217, v182 dst_sel:DWORD dst_unused:UNUSED_PAD src0_sel:BYTE_0 src1_sel:DWORD
	v_max_u32_sdwa v155, v217, v182 dst_sel:DWORD dst_unused:UNUSED_PAD src0_sel:BYTE_1 src1_sel:DWORD
	v_max_u32_sdwa v156, v217, v182 dst_sel:DWORD dst_unused:UNUSED_PAD src0_sel:BYTE_2 src1_sel:DWORD
	v_max_u32_sdwa v157, v217, v182 dst_sel:DWORD dst_unused:UNUSED_PAD src0_sel:BYTE_3 src1_sel:DWORD
	v_cvt_f32_ubyte0_e32 v154, v154
	v_cvt_f32_ubyte0_e32 v155, v155
	v_cvt_f32_ubyte0_e32 v156, v156
	v_cvt_f32_ubyte0_e32 v157, v157
	v_rcp_iflag_f32_e32 v154, v154
	v_rcp_iflag_f32_e32 v155, v155
	v_rcp_iflag_f32_e32 v156, v156
	v_rcp_iflag_f32_e32 v157, v157
	v_cvt_f32_ubyte0_e32 v178, v215
	v_cvt_f32_ubyte1_e32 v179, v215
	v_cvt_f32_ubyte2_e32 v180, v215
	v_cvt_f32_ubyte3_e32 v181, v215
	v_pk_mul_f32 v[154:155], v[154:155], v[178:179]
	v_pk_mul_f32 v[156:157], v[156:157], v[180:181]
	v_pk_mul_f32 v[70:71], v[70:71], v[154:155]
	v_pk_mul_f32 v[72:73], v[72:73], v[156:157]
	s_waitcnt vmcnt(14)
	v_permlane16_swap_b32_e32 v218, v219
	v_permlane16_swap_b32_e32 v220, v221
	s_nop 0
	v_permlane32_swap_b32_e32 v218, v219
	v_permlane32_swap_b32_e32 v220, v221
	v_max_u32_sdwa v154, v220, v182 dst_sel:DWORD dst_unused:UNUSED_PAD src0_sel:BYTE_0 src1_sel:DWORD
	v_max_u32_sdwa v155, v220, v182 dst_sel:DWORD dst_unused:UNUSED_PAD src0_sel:BYTE_1 src1_sel:DWORD
	v_max_u32_sdwa v156, v220, v182 dst_sel:DWORD dst_unused:UNUSED_PAD src0_sel:BYTE_2 src1_sel:DWORD
	v_max_u32_sdwa v157, v220, v182 dst_sel:DWORD dst_unused:UNUSED_PAD src0_sel:BYTE_3 src1_sel:DWORD
	v_cvt_f32_ubyte0_e32 v154, v154
	v_cvt_f32_ubyte0_e32 v155, v155
	v_cvt_f32_ubyte0_e32 v156, v156
	v_cvt_f32_ubyte0_e32 v157, v157
	v_rcp_iflag_f32_e32 v154, v154
	v_rcp_iflag_f32_e32 v155, v155
	v_rcp_iflag_f32_e32 v156, v156
	v_rcp_iflag_f32_e32 v157, v157
	v_cvt_f32_ubyte0_e32 v178, v218
	v_cvt_f32_ubyte1_e32 v179, v218
	v_cvt_f32_ubyte2_e32 v180, v218
	v_cvt_f32_ubyte3_e32 v181, v218
	v_pk_mul_f32 v[154:155], v[154:155], v[178:179]
	v_pk_mul_f32 v[156:157], v[156:157], v[180:181]
	v_pk_mul_f32 v[66:67], v[66:67], v[154:155]
	v_pk_mul_f32 v[68:69], v[68:69], v[156:157]
	v_max_u32_sdwa v154, v221, v182 dst_sel:DWORD dst_unused:UNUSED_PAD src0_sel:BYTE_0 src1_sel:DWORD
	v_max_u32_sdwa v155, v221, v182 dst_sel:DWORD dst_unused:UNUSED_PAD src0_sel:BYTE_1 src1_sel:DWORD
	v_max_u32_sdwa v156, v221, v182 dst_sel:DWORD dst_unused:UNUSED_PAD src0_sel:BYTE_2 src1_sel:DWORD
	v_max_u32_sdwa v157, v221, v182 dst_sel:DWORD dst_unused:UNUSED_PAD src0_sel:BYTE_3 src1_sel:DWORD
	v_cvt_f32_ubyte0_e32 v154, v154
	v_cvt_f32_ubyte0_e32 v155, v155
	v_cvt_f32_ubyte0_e32 v156, v156
	v_cvt_f32_ubyte0_e32 v157, v157
	v_rcp_iflag_f32_e32 v154, v154
	v_rcp_iflag_f32_e32 v155, v155
	v_rcp_iflag_f32_e32 v156, v156
	v_rcp_iflag_f32_e32 v157, v157
	v_cvt_f32_ubyte0_e32 v178, v219
	v_cvt_f32_ubyte1_e32 v179, v219
	v_cvt_f32_ubyte2_e32 v180, v219
	v_cvt_f32_ubyte3_e32 v181, v219
	v_pk_mul_f32 v[154:155], v[154:155], v[178:179]
	v_pk_mul_f32 v[156:157], v[156:157], v[180:181]
	v_pk_mul_f32 v[62:63], v[62:63], v[154:155]
	v_pk_mul_f32 v[64:65], v[64:65], v[156:157]
	s_waitcnt vmcnt(12)
	v_permlane16_swap_b32_e32 v222, v223
	v_permlane16_swap_b32_e32 v224, v225
	s_nop 0
	v_permlane32_swap_b32_e32 v222, v223
	v_permlane32_swap_b32_e32 v224, v225
	v_max_u32_sdwa v154, v224, v182 dst_sel:DWORD dst_unused:UNUSED_PAD src0_sel:BYTE_0 src1_sel:DWORD
	v_max_u32_sdwa v155, v224, v182 dst_sel:DWORD dst_unused:UNUSED_PAD src0_sel:BYTE_1 src1_sel:DWORD
	v_max_u32_sdwa v156, v224, v182 dst_sel:DWORD dst_unused:UNUSED_PAD src0_sel:BYTE_2 src1_sel:DWORD
	v_max_u32_sdwa v157, v224, v182 dst_sel:DWORD dst_unused:UNUSED_PAD src0_sel:BYTE_3 src1_sel:DWORD
	v_cvt_f32_ubyte0_e32 v154, v154
	v_cvt_f32_ubyte0_e32 v155, v155
	v_cvt_f32_ubyte0_e32 v156, v156
	v_cvt_f32_ubyte0_e32 v157, v157
	v_rcp_iflag_f32_e32 v154, v154
	v_rcp_iflag_f32_e32 v155, v155
	v_rcp_iflag_f32_e32 v156, v156
	v_rcp_iflag_f32_e32 v157, v157
	v_cvt_f32_ubyte0_e32 v178, v222
	v_cvt_f32_ubyte1_e32 v179, v222
	v_cvt_f32_ubyte2_e32 v180, v222
	v_cvt_f32_ubyte3_e32 v181, v222
	v_pk_mul_f32 v[154:155], v[154:155], v[178:179]
	v_pk_mul_f32 v[156:157], v[156:157], v[180:181]
	v_pk_mul_f32 v[58:59], v[58:59], v[154:155]
	v_pk_mul_f32 v[60:61], v[60:61], v[156:157]
	v_max_u32_sdwa v154, v225, v182 dst_sel:DWORD dst_unused:UNUSED_PAD src0_sel:BYTE_0 src1_sel:DWORD
	v_max_u32_sdwa v155, v225, v182 dst_sel:DWORD dst_unused:UNUSED_PAD src0_sel:BYTE_1 src1_sel:DWORD
	v_max_u32_sdwa v156, v225, v182 dst_sel:DWORD dst_unused:UNUSED_PAD src0_sel:BYTE_2 src1_sel:DWORD
	v_max_u32_sdwa v157, v225, v182 dst_sel:DWORD dst_unused:UNUSED_PAD src0_sel:BYTE_3 src1_sel:DWORD
	v_cvt_f32_ubyte0_e32 v154, v154
	v_cvt_f32_ubyte0_e32 v155, v155
	v_cvt_f32_ubyte0_e32 v156, v156
	v_cvt_f32_ubyte0_e32 v157, v157
	v_rcp_iflag_f32_e32 v154, v154
	v_rcp_iflag_f32_e32 v155, v155
	v_rcp_iflag_f32_e32 v156, v156
	v_rcp_iflag_f32_e32 v157, v157
	v_cvt_f32_ubyte0_e32 v178, v223
	v_cvt_f32_ubyte1_e32 v179, v223
	v_cvt_f32_ubyte2_e32 v180, v223
	v_cvt_f32_ubyte3_e32 v181, v223
	v_pk_mul_f32 v[154:155], v[154:155], v[178:179]
	v_pk_mul_f32 v[156:157], v[156:157], v[180:181]
	v_pk_mul_f32 v[54:55], v[54:55], v[154:155]
	v_pk_mul_f32 v[56:57], v[56:57], v[156:157]
	s_waitcnt vmcnt(10)
;   DI void mid(f32x4 (&acc)[2][2][4][2], const pg8::Unit& u, int wr, int wc, int fr, int fq) const {
; #pragma unroll
;     for (int ai = 0; ai < 2; ++ai)
; #pragma unroll
;       for (int m = 0; m < 4; ++m) {
;         int row = u.pm * 256 + 128 * ai + 64 * wr + 16 * m + fr;
;         asm volatile("" : "+v"(row));
; #pragma unroll
;         for (int bj = 0; bj < 2; ++bj)
; #pragma unroll
;           for (int n = 0; n < 2; ++n) {
;             const size_t idx = (size_t)row * 1024 + u.pn * 256 + 128 * bj + 32 * wc + 16 * n + 4 * fq;
;             const unsigned ga = *reinterpret_cast<const unsigned*>(reinterpret_cast<const unsigned char*>(p.ws + OFF_RA) + idx);
;             const unsigned gb = *reinterpret_cast<const unsigned*>(reinterpret_cast<const unsigned char*>(p.ws + OFF_RB) + idx);
; #pragma unroll
;             for (int j = 0; j < 4; ++j) {
;               const unsigned a8 = (ga >> (8 * j)) & 255u, b8 = (gb >> (8 * j)) & 255u;
;               acc[ai][bj][m][n][j] *= (float)a8 * __builtin_amdgcn_rcpf((float)(b8 > 1u ? b8 : 1u));
;             }
;           }
	v_permlane16_swap_b32_e32 v226, v227
	v_permlane16_swap_b32_e32 v228, v229
	s_nop 0
	v_permlane32_swap_b32_e32 v226, v227
	v_permlane32_swap_b32_e32 v228, v229
	v_max_u32_sdwa v154, v228, v182 dst_sel:DWORD dst_unused:UNUSED_PAD src0_sel:BYTE_0 src1_sel:DWORD
	v_max_u32_sdwa v155, v228, v182 dst_sel:DWORD dst_unused:UNUSED_PAD src0_sel:BYTE_1 src1_sel:DWORD
	v_max_u32_sdwa v156, v228, v182 dst_sel:DWORD dst_unused:UNUSED_PAD src0_sel:BYTE_2 src1_sel:DWORD
	v_max_u32_sdwa v157, v228, v182 dst_sel:DWORD dst_unused:UNUSED_PAD src0_sel:BYTE_3 src1_sel:DWORD
	v_cvt_f32_ubyte0_e32 v154, v154
	v_cvt_f32_ubyte0_e32 v155, v155
	v_cvt_f32_ubyte0_e32 v156, v156
	v_cvt_f32_ubyte0_e32 v157, v157
	v_rcp_iflag_f32_e32 v154, v154
	v_rcp_iflag_f32_e32 v155, v155
	v_rcp_iflag_f32_e32 v156, v156
	v_rcp_iflag_f32_e32 v157, v157
	v_cvt_f32_ubyte0_e32 v178, v226
	v_cvt_f32_ubyte1_e32 v179, v226
	v_cvt_f32_ubyte2_e32 v180, v226
	v_cvt_f32_ubyte3_e32 v181, v226
	v_pk_mul_f32 v[154:155], v[154:155], v[178:179]
	v_pk_mul_f32 v[156:157], v[156:157], v[180:181]
	v_pk_mul_f32 v[50:51], v[50:51], v[154:155]
	v_pk_mul_f32 v[52:53], v[52:53], v[156:157]
	v_max_u32_sdwa v154, v229, v182 dst_sel:DWORD dst_unused:UNUSED_PAD src0_sel:BYTE_0 src1_sel:DWORD
	v_max_u32_sdwa v155, v229, v182 dst_sel:DWORD dst_unused:UNUSED_PAD src0_sel:BYTE_1 src1_sel:DWORD
	v_max_u32_sdwa v156, v229, v182 dst_sel:DWORD dst_unused:UNUSED_PAD src0_sel:BYTE_2 src1_sel:DWORD
	v_max_u32_sdwa v157, v229, v182 dst_sel:DWORD dst_unused:UNUSED_PAD src0_sel:BYTE_3 src1_sel:DWORD
	v_cvt_f32_ubyte0_e32 v154, v154
	v_cvt_f32_ubyte0_e32 v155, v155
	v_cvt_f32_ubyte0_e32 v156, v156
	v_cvt_f32_ubyte0_e32 v157, v157
	v_rcp_iflag_f32_e32 v154, v154
	v_rcp_iflag_f32_e32 v155, v155
	v_rcp_iflag_f32_e32 v156, v156
	v_rcp_iflag_f32_e32 v157, v157
	v_cvt_f32_ubyte0_e32 v178, v227
	v_cvt_f32_ubyte1_e32 v179, v227
	v_cvt_f32_ubyte2_e32 v180, v227
	v_cvt_f32_ubyte3_e32 v181, v227
	v_pk_mul_f32 v[154:155], v[154:155], v[178:179]
	v_pk_mul_f32 v[156:157], v[156:157], v[180:181]
	v_pk_mul_f32 v[46:47], v[46:47], v[154:155]
	v_pk_mul_f32 v[48:49], v[48:49], v[156:157]
	s_waitcnt vmcnt(8)
	v_permlane16_swap_b32_e32 v230, v231
	v_permlane16_swap_b32_e32 v232, v233
	s_nop 0
	v_permlane32_swap_b32_e32 v230, v231
	v_permlane32_swap_b32_e32 v232, v233
	v_max_u32_sdwa v154, v232, v182 dst_sel:DWORD dst_unused:UNUSED_PAD src0_sel:BYTE_0 src1_sel:DWORD
	v_max_u32_sdwa v155, v232, v182 dst_sel:DWORD dst_unused:UNUSED_PAD src0_sel:BYTE_1 src1_sel:DWORD
	v_max_u32_sdwa v156, v232, v182 dst_sel:DWORD dst_unused:UNUSED_PAD src0_sel:BYTE_2 src1_sel:DWORD
	v_max_u32_sdwa v157, v232, v182 dst_sel:DWORD dst_unused:UNUSED_PAD src0_sel:BYTE_3 src1_sel:DWORD
	v_cvt_f32_ubyte0_e32 v154, v154
	v_cvt_f32_ubyte0_e32 v155, v155
	v_cvt_f32_ubyte0_e32 v156, v156
	v_cvt_f32_ubyte0_e32 v157, v157
	v_rcp_iflag_f32_e32 v154, v154
	v_rcp_iflag_f32_e32 v155, v155
	v_rcp_iflag_f32_e32 v156, v156
	v_rcp_iflag_f32_e32 v157, v157
	v_cvt_f32_ubyte0_e32 v178, v230
	v_cvt_f32_ubyte1_e32 v179, v230
	v_cvt_f32_ubyte2_e32 v180, v230
	v_cvt_f32_ubyte3_e32 v181, v230
	v_pk_mul_f32 v[154:155], v[154:155], v[178:179]
	v_pk_mul_f32 v[156:157], v[156:157], v[180:181]
	v_pk_mul_f32 v[42:43], v[42:43], v[154:155]
	v_pk_mul_f32 v[44:45], v[44:45], v[156:157]
	v_max_u32_sdwa v154, v233, v182 dst_sel:DWORD dst_unused:UNUSED_PAD src0_sel:BYTE_0 src1_sel:DWORD
	v_max_u32_sdwa v155, v233, v182 dst_sel:DWORD dst_unused:UNUSED_PAD src0_sel:BYTE_1 src1_sel:DWORD
	v_max_u32_sdwa v156, v233, v182 dst_sel:DWORD dst_unused:UNUSED_PAD src0_sel:BYTE_2 src1_sel:DWORD
	v_max_u32_sdwa v157, v233, v182 dst_sel:DWORD dst_unused:UNUSED_PAD src0_sel:BYTE_3 src1_sel:DWORD
	v_cvt_f32_ubyte0_e32 v154, v154
	v_cvt_f32_ubyte0_e32 v155, v155
	v_cvt_f32_ubyte0_e32 v156, v156
	v_cvt_f32_ubyte0_e32 v157, v157
	v_rcp_iflag_f32_e32 v154, v154
	v_rcp_iflag_f32_e32 v155, v155
	v_rcp_iflag_f32_e32 v156, v156
	v_rcp_iflag_f32_e32 v157, v157
	v_cvt_f32_ubyte0_e32 v178, v231
	v_cvt_f32_ubyte1_e32 v179, v231
	v_cvt_f32_ubyte2_e32 v180, v231
	v_cvt_f32_ubyte3_e32 v181, v231
	v_pk_mul_f32 v[154:155], v[154:155], v[178:179]
	v_pk_mul_f32 v[156:157], v[156:157], v[180:181]
	v_pk_mul_f32 v[38:39], v[38:39], v[154:155]
	v_pk_mul_f32 v[40:41], v[40:41], v[156:157]
	s_waitcnt vmcnt(6)
	v_permlane16_swap_b32_e32 v186, v187
	v_permlane16_swap_b32_e32 v188, v189
	s_nop 0
	v_permlane32_swap_b32_e32 v186, v187
	v_permlane32_swap_b32_e32 v188, v189
	v_max_u32_sdwa v154, v188, v182 dst_sel:DWORD dst_unused:UNUSED_PAD src0_sel:BYTE_0 src1_sel:DWORD
	v_max_u32_sdwa v155, v188, v182 dst_sel:DWORD dst_unused:UNUSED_PAD src0_sel:BYTE_1 src1_sel:DWORD
	v_max_u32_sdwa v156, v188, v182 dst_sel:DWORD dst_unused:UNUSED_PAD src0_sel:BYTE_2 src1_sel:DWORD
	v_max_u32_sdwa v157, v188, v182 dst_sel:DWORD dst_unused:UNUSED_PAD src0_sel:BYTE_3 src1_sel:DWORD
	v_cvt_f32_ubyte0_e32 v154, v154
	v_cvt_f32_ubyte0_e32 v155, v155
	v_cvt_f32_ubyte0_e32 v156, v156
	v_cvt_f32_ubyte0_e32 v157, v157
	v_rcp_iflag_f32_e32 v154, v154
	v_rcp_iflag_f32_e32 v155, v155
	v_rcp_iflag_f32_e32 v156, v156
	v_rcp_iflag_f32_e32 v157, v157
	v_cvt_f32_ubyte0_e32 v178, v186
	v_cvt_f32_ubyte1_e32 v179, v186
	v_cvt_f32_ubyte2_e32 v180, v186
	v_cvt_f32_ubyte3_e32 v181, v186
	v_pk_mul_f32 v[154:155], v[154:155], v[178:179]
	v_pk_mul_f32 v[156:157], v[156:157], v[180:181]
	v_pk_mul_f32 v[34:35], v[34:35], v[154:155]
	v_pk_mul_f32 v[36:37], v[36:37], v[156:157]
	v_max_u32_sdwa v154, v189, v182 dst_sel:DWORD dst_unused:UNUSED_PAD src0_sel:BYTE_0 src1_sel:DWORD
	v_max_u32_sdwa v155, v189, v182 dst_sel:DWORD dst_unused:UNUSED_PAD src0_sel:BYTE_1 src1_sel:DWORD
	v_max_u32_sdwa v156, v189, v182 dst_sel:DWORD dst_unused:UNUSED_PAD src0_sel:BYTE_2 src1_sel:DWORD
	v_max_u32_sdwa v157, v189, v182 dst_sel:DWORD dst_unused:UNUSED_PAD src0_sel:BYTE_3 src1_sel:DWORD
	v_cvt_f32_ubyte0_e32 v154, v154
	v_cvt_f32_ubyte0_e32 v155, v155
	v_cvt_f32_ubyte0_e32 v156, v156
	v_cvt_f32_ubyte0_e32 v157, v157
	v_rcp_iflag_f32_e32 v154, v154
	v_rcp_iflag_f32_e32 v155, v155
	v_rcp_iflag_f32_e32 v156, v156
	v_rcp_iflag_f32_e32 v157, v157
	v_cvt_f32_ubyte0_e32 v178, v187
	v_cvt_f32_ubyte1_e32 v179, v187
	v_cvt_f32_ubyte2_e32 v180, v187
	v_cvt_f32_ubyte3_e32 v181, v187
	v_pk_mul_f32 v[154:155], v[154:155], v[178:179]
	v_pk_mul_f32 v[156:157], v[156:157], v[180:181]
	v_pk_mul_f32 v[30:31], v[30:31], v[154:155]
	v_pk_mul_f32 v[32:33], v[32:33], v[156:157]
	s_waitcnt vmcnt(4)
; template <class Epi, class Sched>
; __device__ __forceinline__ void gemm_phase(PG8_LAS unsigned char* lds, const Gemm g, const Sched& S, const Epi& E) {
;     ...
;         for (int t = 0; t < nt; t += 2) {
;             const bool last = (t == nt - 2);
;             const char* a1 = cA + (size_t)(t + 1) * kstep;
;             const char* a2 = last ? nA : cA + (size_t)(t + 2) * kstep; const char* b2 = last ? nB : cB + (size_t)(t + 2) * kstep;
;             const char* a3 = a2 + kstep; const char* b3 = b2 + kstep;
;             if (last && has_next) S.a_ready(nxt);
;             if constexpr (Epi::MIDK) { if (t == nt / 2) E.mid(acc, cur, wr, wc, fr, fq); }
;             PG8_LDB(B0, 0, 0); PG8_SCHED; PG8_LDA(At, 0, 0); PG8_STAGE(PG8_SA(1, 1), a1 + hstep, voffA);
;             PG8_WAIT_L(8); PG8_BAR; PG8_WAIT_L(0); PG8_MMA(0, 0, At, B0); PG8_BAR; PG8_SCHED;
;             PG8_LDB(B1, 0, 1); PG8_STAGE(PG8_SB(0, 0), b2, voffB);
;             PG8_BAR; PG8_WAIT_L(0); PG8_MMA(0, 1, At, B1); PG8_BAR;
;             PG8_LDA(At, 0, 1); PG8_STAGE(PG8_SA(0, 0), a2, voffA);
;             PG8_BAR; PG8_WAIT_L(0); PG8_MMA(1, 0, At, B0); PG8_BAR; PG8_SCHED;
;             PG8_STAGE(PG8_SB(0, 1), b2 + hstep, voffB);
;             PG8_WAIT_V(6); PG8_BAR; PG8_MMA(1, 1, At, B1); PG8_BAR;
;   DI void mid(f32x4 (&acc)[2][2][4][2], const pg8::Unit& u, int wr, int wc, int fr, int fq) const {
; #pragma unroll
;     for (int ai = 0; ai < 2; ++ai)
; #pragma unroll
;       for (int m = 0; m < 4; ++m) {
;         int row = u.pm * 256 + 128 * ai + 64 * wr + 16 * m + fr;
;         asm volatile("" : "+v"(row));
; #pragma unroll
;         for (int bj = 0; bj < 2; ++bj)
; #pragma unroll
;           for (int n = 0; n < 2; ++n) {
;             const size_t idx = (size_t)row * 1024 + u.pn * 256 + 128 * bj + 32 * wc + 16 * n + 4 * fq;
;             const unsigned ga = *reinterpret_cast<const unsigned*>(reinterpret_cast<const unsigned char*>(p.ws + OFF_RA) + idx);
;             const unsigned gb = *reinterpret_cast<const unsigned*>(reinterpret_cast<const unsigned char*>(p.ws + OFF_RB) + idx);
; #pragma unroll
;             for (int j = 0; j < 4; ++j) {
;               const unsigned a8 = (ga >> (8 * j)) & 255u, b8 = (gb >> (8 * j)) & 255u;
;               acc[ai][bj][m][n][j] *= (float)a8 * __builtin_amdgcn_rcpf((float)(b8 > 1u ? b8 : 1u));
;             }
;           }
	v_permlane16_swap_b32_e32 v190, v191
	v_permlane16_swap_b32_e32 v192, v193
	s_nop 0
	v_permlane32_swap_b32_e32 v190, v191
	v_permlane32_swap_b32_e32 v192, v193
	v_max_u32_sdwa v154, v192, v182 dst_sel:DWORD dst_unused:UNUSED_PAD src0_sel:BYTE_0 src1_sel:DWORD
	v_max_u32_sdwa v155, v192, v182 dst_sel:DWORD dst_unused:UNUSED_PAD src0_sel:BYTE_1 src1_sel:DWORD
	v_max_u32_sdwa v156, v192, v182 dst_sel:DWORD dst_unused:UNUSED_PAD src0_sel:BYTE_2 src1_sel:DWORD
	v_max_u32_sdwa v157, v192, v182 dst_sel:DWORD dst_unused:UNUSED_PAD src0_sel:BYTE_3 src1_sel:DWORD
	v_cvt_f32_ubyte0_e32 v154, v154
	v_cvt_f32_ubyte0_e32 v155, v155
	v_cvt_f32_ubyte0_e32 v156, v156
	v_cvt_f32_ubyte0_e32 v157, v157
	v_rcp_iflag_f32_e32 v154, v154
	v_rcp_iflag_f32_e32 v155, v155
	v_rcp_iflag_f32_e32 v156, v156
	v_rcp_iflag_f32_e32 v157, v157
	v_cvt_f32_ubyte0_e32 v178, v190
	v_cvt_f32_ubyte1_e32 v179, v190
	v_cvt_f32_ubyte2_e32 v180, v190
	v_cvt_f32_ubyte3_e32 v181, v190
	v_pk_mul_f32 v[154:155], v[154:155], v[178:179]
	v_pk_mul_f32 v[156:157], v[156:157], v[180:181]
	v_pk_mul_f32 v[26:27], v[26:27], v[154:155]
	v_pk_mul_f32 v[28:29], v[28:29], v[156:157]
	v_max_u32_sdwa v154, v193, v182 dst_sel:DWORD dst_unused:UNUSED_PAD src0_sel:BYTE_0 src1_sel:DWORD
	v_max_u32_sdwa v155, v193, v182 dst_sel:DWORD dst_unused:UNUSED_PAD src0_sel:BYTE_1 src1_sel:DWORD
	v_max_u32_sdwa v156, v193, v182 dst_sel:DWORD dst_unused:UNUSED_PAD src0_sel:BYTE_2 src1_sel:DWORD
	v_max_u32_sdwa v157, v193, v182 dst_sel:DWORD dst_unused:UNUSED_PAD src0_sel:BYTE_3 src1_sel:DWORD
	v_cvt_f32_ubyte0_e32 v154, v154
	v_cvt_f32_ubyte0_e32 v155, v155
	v_cvt_f32_ubyte0_e32 v156, v156
	v_cvt_f32_ubyte0_e32 v157, v157
	v_rcp_iflag_f32_e32 v154, v154
	v_rcp_iflag_f32_e32 v155, v155
	v_rcp_iflag_f32_e32 v156, v156
	v_rcp_iflag_f32_e32 v157, v157
	v_cvt_f32_ubyte0_e32 v178, v191
	v_cvt_f32_ubyte1_e32 v179, v191
	v_cvt_f32_ubyte2_e32 v180, v191
	v_cvt_f32_ubyte3_e32 v181, v191
	v_pk_mul_f32 v[154:155], v[154:155], v[178:179]
	v_pk_mul_f32 v[156:157], v[156:157], v[180:181]
	v_pk_mul_f32 v[22:23], v[22:23], v[154:155]
	v_pk_mul_f32 v[24:25], v[24:25], v[156:157]
	s_waitcnt vmcnt(2)
	v_permlane16_swap_b32_e32 v194, v195
	v_permlane16_swap_b32_e32 v196, v197
	s_nop 0
	v_permlane32_swap_b32_e32 v194, v195
	v_permlane32_swap_b32_e32 v196, v197
	v_max_u32_sdwa v154, v196, v182 dst_sel:DWORD dst_unused:UNUSED_PAD src0_sel:BYTE_0 src1_sel:DWORD
	v_max_u32_sdwa v155, v196, v182 dst_sel:DWORD dst_unused:UNUSED_PAD src0_sel:BYTE_1 src1_sel:DWORD
	v_max_u32_sdwa v156, v196, v182 dst_sel:DWORD dst_unused:UNUSED_PAD src0_sel:BYTE_2 src1_sel:DWORD
	v_max_u32_sdwa v157, v196, v182 dst_sel:DWORD dst_unused:UNUSED_PAD src0_sel:BYTE_3 src1_sel:DWORD
	v_cvt_f32_ubyte0_e32 v154, v154
	v_cvt_f32_ubyte0_e32 v155, v155
	v_cvt_f32_ubyte0_e32 v156, v156
	v_cvt_f32_ubyte0_e32 v157, v157
	v_rcp_iflag_f32_e32 v154, v154
	v_rcp_iflag_f32_e32 v155, v155
	v_rcp_iflag_f32_e32 v156, v156
	v_rcp_iflag_f32_e32 v157, v157
	v_cvt_f32_ubyte0_e32 v178, v194
	v_cvt_f32_ubyte1_e32 v179, v194
	v_cvt_f32_ubyte2_e32 v180, v194
	v_cvt_f32_ubyte3_e32 v181, v194
	v_pk_mul_f32 v[154:155], v[154:155], v[178:179]
	v_pk_mul_f32 v[156:157], v[156:157], v[180:181]
	v_pk_mul_f32 v[12:13], v[12:13], v[154:155]
	v_pk_mul_f32 v[14:15], v[14:15], v[156:157]
	v_max_u32_sdwa v154, v197, v182 dst_sel:DWORD dst_unused:UNUSED_PAD src0_sel:BYTE_0 src1_sel:DWORD
	v_max_u32_sdwa v155, v197, v182 dst_sel:DWORD dst_unused:UNUSED_PAD src0_sel:BYTE_1 src1_sel:DWORD
	v_max_u32_sdwa v156, v197, v182 dst_sel:DWORD dst_unused:UNUSED_PAD src0_sel:BYTE_2 src1_sel:DWORD
	v_max_u32_sdwa v157, v197, v182 dst_sel:DWORD dst_unused:UNUSED_PAD src0_sel:BYTE_3 src1_sel:DWORD
	v_cvt_f32_ubyte0_e32 v154, v154
	v_cvt_f32_ubyte0_e32 v155, v155
	v_cvt_f32_ubyte0_e32 v156, v156
	v_cvt_f32_ubyte0_e32 v157, v157
	v_rcp_iflag_f32_e32 v154, v154
	v_rcp_iflag_f32_e32 v155, v155
	v_rcp_iflag_f32_e32 v156, v156
	v_rcp_iflag_f32_e32 v157, v157
	v_cvt_f32_ubyte0_e32 v178, v195
	v_cvt_f32_ubyte1_e32 v179, v195
	v_cvt_f32_ubyte2_e32 v180, v195
	v_cvt_f32_ubyte3_e32 v181, v195
	v_pk_mul_f32 v[154:155], v[154:155], v[178:179]
	v_pk_mul_f32 v[156:157], v[156:157], v[180:181]
	v_pk_mul_f32 v[8:9], v[8:9], v[154:155]
	v_pk_mul_f32 v[10:11], v[10:11], v[156:157]
	s_waitcnt vmcnt(0)
	v_permlane16_swap_b32_e32 v198, v199
	v_permlane16_swap_b32_e32 v200, v201
	s_nop 0
	v_permlane32_swap_b32_e32 v198, v199
	v_permlane32_swap_b32_e32 v200, v201
	v_max_u32_sdwa v154, v200, v182 dst_sel:DWORD dst_unused:UNUSED_PAD src0_sel:BYTE_0 src1_sel:DWORD
	v_max_u32_sdwa v155, v200, v182 dst_sel:DWORD dst_unused:UNUSED_PAD src0_sel:BYTE_1 src1_sel:DWORD
	v_max_u32_sdwa v156, v200, v182 dst_sel:DWORD dst_unused:UNUSED_PAD src0_sel:BYTE_2 src1_sel:DWORD
	v_max_u32_sdwa v157, v200, v182 dst_sel:DWORD dst_unused:UNUSED_PAD src0_sel:BYTE_3 src1_sel:DWORD
	v_cvt_f32_ubyte0_e32 v154, v154
	v_cvt_f32_ubyte0_e32 v155, v155
	v_cvt_f32_ubyte0_e32 v156, v156
	v_cvt_f32_ubyte0_e32 v157, v157
	v_rcp_iflag_f32_e32 v154, v154
	v_rcp_iflag_f32_e32 v155, v155
	v_rcp_iflag_f32_e32 v156, v156
	v_rcp_iflag_f32_e32 v157, v157
	v_cvt_f32_ubyte0_e32 v178, v198
	v_cvt_f32_ubyte1_e32 v179, v198
	v_cvt_f32_ubyte2_e32 v180, v198
	v_cvt_f32_ubyte3_e32 v181, v198
	v_pk_mul_f32 v[154:155], v[154:155], v[178:179]
	v_pk_mul_f32 v[156:157], v[156:157], v[180:181]
	v_pk_mul_f32 v[4:5], v[4:5], v[154:155]
	v_pk_mul_f32 v[6:7], v[6:7], v[156:157]
	v_max_u32_sdwa v154, v201, v182 dst_sel:DWORD dst_unused:UNUSED_PAD src0_sel:BYTE_0 src1_sel:DWORD
	v_max_u32_sdwa v155, v201, v182 dst_sel:DWORD dst_unused:UNUSED_PAD src0_sel:BYTE_1 src1_sel:DWORD
	v_max_u32_sdwa v156, v201, v182 dst_sel:DWORD dst_unused:UNUSED_PAD src0_sel:BYTE_2 src1_sel:DWORD
	v_max_u32_sdwa v157, v201, v182 dst_sel:DWORD dst_unused:UNUSED_PAD src0_sel:BYTE_3 src1_sel:DWORD
	v_cvt_f32_ubyte0_e32 v154, v154
	v_cvt_f32_ubyte0_e32 v155, v155
	v_cvt_f32_ubyte0_e32 v156, v156
	v_cvt_f32_ubyte0_e32 v157, v157
	v_rcp_iflag_f32_e32 v154, v154
	v_rcp_iflag_f32_e32 v155, v155
	v_rcp_iflag_f32_e32 v156, v156
	v_rcp_iflag_f32_e32 v157, v157
	v_cvt_f32_ubyte0_e32 v178, v199
	v_cvt_f32_ubyte1_e32 v179, v199
	v_cvt_f32_ubyte2_e32 v180, v199
	v_cvt_f32_ubyte3_e32 v181, v199
	v_pk_mul_f32 v[154:155], v[154:155], v[178:179]
	v_pk_mul_f32 v[156:157], v[156:157], v[180:181]
	v_pk_mul_f32 v[0:1], v[0:1], v[154:155]
	v_pk_mul_f32 v[2:3], v[2:3], v[156:157]
	s_branch .LBB0_2735
